# GEMM K-loops: LDS-DMA tile loads addressed as SGPR base + 32-bit lane offset (no per-load 64-bit VALU address adds); in-projection K-loop fully converted
# speedup vs baseline: 1.0615x; 1.0007x over previous
; #define PG8_STAGE(bufoff, gbase, voff) do { _Pragma("unroll") for (int _i = 0; _i < 2; ++_i) \
;         __builtin_amdgcn_global_load_lds((const unsigned*)((const char*)(gbase) + (voff)[_i]), (LAS unsigned*)(lds + (bufoff) + ldsw + _i * 8192), 16, 0, 0); } while (0)
; #define PG8_WAIT_V(n) asm volatile("s_waitcnt vmcnt(" #n ")" ::: "memory")
; #define PG8_BAR __builtin_amdgcn_s_barrier()
; template <class Epi, bool PERM = true, bool DBLK = false>
; __device__ __forceinline__ void gemm_phase(LAS unsigned char* lds, const Gemm g, const StaticOrder& S, const Epi& E, const int tid) {
;     ...
;     for (int i = 0; i < 2; ++i) { int R, C; stage_rc(tid * 16 + i * 8192, R, C); const int Rb = PERM ? ((R & ~31) + perm32(R & 31)) : R;
;         voffA[i] = (unsigned)(R * K + C) * 2u; voffB[i] = (unsigned)(Rb * K + C) * 2u; }
;     const size_t kstep = (size_t)(BK * 2);
;     const size_t hstep = (size_t)HALF * K * 2;
;     const size_t tstep = 2 * hstep;
;     const unsigned ldsw = (unsigned)wid * 1024u;
;     const int aoff = lds_byte(wr * 64 + fr, fq * 8), boff = lds_byte(wc * 32 + fr, fq * 8);
;     ...
;     Unit cur, nxt; int ui = 0;
;     if (!S.next(0, cur)) return;
;     f32x4 acc[2][2][4][2];
; #pragma unroll
;     for (int a = 0; a < 2; ++a)
; #pragma unroll
;         for (int b = 0; b < 2; ++b)
; #pragma unroll
;             for (int m = 0; m < 4; ++m)
; #pragma unroll
;                 for (int n = 0; n < 2; ++n) acc[a][b][m][n] = (f32x4){0.f, 0.f, 0.f, 0.f};
;     bf16x8 At[4][2], B0[2][2], B1[2][2];
;     const char* cA = (const char*)g.A + (size_t)cur.pm * tstep; const char* cB = (const char*)g.Bt + (size_t)cur.pn * tstep;
;     PG8_STAGE(PG8_SB(0, 0), cB, voffB); PG8_STAGE(PG8_SB(0, 1), cB + hstep, voffB); PG8_STAGE(PG8_SA(0, 0), cA, voffA); PG8_STAGE(PG8_SA(0, 1), cA + hstep, voffA);
;     if (wr == 1) PG8_BAR;
;     PG8_WAIT_V(2); PG8_BAR;
;     PG8_STAGE(PG8_SB(1, 0), cB + kstep, voffB); PG8_STAGE(PG8_SA(1, 0), cA + kstep, voffA); PG8_STAGE(PG8_SB(1, 1), cB + hstep + kstep, voffB);
;     PG8_WAIT_V(6); PG8_BAR;
.LBB0_203:
	s_add_u32 s14, s0, 0x2500000
	s_addc_u32 s15, s1, 0
	s_and_b64 s[16:17], s[10:11], exec
	v_readlane_b32 s5, v254, 24
	s_cselect_b32 s89, s68, s5
	s_add_u32 s16, s0, 0x4600000
	s_addc_u32 s17, s1, 0
	s_add_u32 s18, s0, 0x8600000
	s_addc_u32 s19, s1, 0
	s_add_u32 s22, s0, 0x8e00000
	s_addc_u32 s23, s1, 0
	s_lshl_b32 s0, s27, 5
	s_and_b32 s87, s0, 0x60
	s_add_i32 m0, s21, 0x18000
	v_lshl_add_u64 v[8:9], v[8:9], 0, s[84:85]
	s_lshl_b32 s86, s26, 6
	s_lshl_b32 s5, s26, 13
	s_lshl_b32 s26, s87, 7
	s_waitcnt vmcnt(2)
	s_barrier
	global_load_lds_dwordx4 v[8:9], off
	v_lshl_add_u64 v[6:7], v[6:7], 0, s[84:85]
	s_add_i32 m0, s21, 0x1a000
	s_add_i32 s62, s21, 0x8000
	s_add_i32 s63, s21, 0xa000
	global_load_lds_dwordx4 v[6:7], off
	v_lshl_add_u64 v[2:3], v[2:3], 0, s[84:85]
	s_mov_b32 m0, s62
	s_add_u32 s0, s74, 0x40080
	global_load_lds_dwordx4 v[2:3], off
	v_lshl_add_u64 v[2:3], v[4:5], 0, s[84:85]
	s_mov_b32 m0, s63
	s_addc_u32 s1, s75, 0
	global_load_lds_dwordx4 v[2:3], off
	s_add_i32 m0, s21, 0x1c000
	s_nop 0
	global_load_lds_dwordx4 v0, s[0:1]
	v_lshl_add_u64 v[2:3], s[0:1], 0, v[150:151]
	s_add_i32 m0, s21, 0x1e000
	s_movk_i32 s0, 0x3c0
	global_load_lds_dwordx4 v[2:3], off
	v_and_b32_e32 v2, 48, v10
	v_lshlrev_b32_e32 v3, 6, v10
	v_and_or_b32 v2, v3, s0, v2
	v_lshlrev_b32_e32 v3, 2, v10
	v_and_b32_e32 v3, 32, v3
	v_bitop3_b32 v4, v2, s5, v3 bitop3:0xde
	v_bitop3_b32 v163, s26, v2, v3 bitop3:0xf6
	v_lshlrev_b32_e32 v2, 14, v14
	v_and_b32_e32 v2, 0xffff8000, v2
	v_lshl_add_u32 v2, v15, 11, v2
	v_and_b32_e32 v3, 1, v14
	v_lshl_or_b32 v2, v3, 6, v2
	v_lshl_add_u32 v152, v16, 1, v2
	v_lshlrev_b32_e32 v2, 14, v11
	v_and_b32_e32 v2, 0xffff8000, v2
	s_waitcnt vmcnt(6)
	v_lshl_add_u32 v2, v12, 11, v2
	v_and_b32_e32 v3, 1, v11
	s_cmpk_lt_u32 s3, 0x100
	v_lshl_or_b32 v2, v3, 6, v2
	s_cselect_b64 s[26:27], -1, 0
	s_ashr_i32 s78, s89, 31
	s_ashr_i32 s79, s2, 31
	v_mov_b32_e32 v153, v1
	v_lshl_add_u32 v154, v13, 1, v2
	v_mov_b32_e32 v155, v1
	s_mov_b32 s3, 0
	v_mov_b64_e32 v[156:157], s[92:93]
	v_add_u32_e32 v165, 0, v4
	s_barrier
	s_branch .LBB0_206

; #define PG8_STAGE(bufoff, gbase, voff) do { _Pragma("unroll") for (int _i = 0; _i < 2; ++_i) \
;         __builtin_amdgcn_global_load_lds((const unsigned*)((const char*)(gbase) + (voff)[_i]), (LAS unsigned*)(lds + (bufoff) + ldsw + _i * 8192), 16, 0, 0); } while (0)
; #define PG8_LDA(dst, b, h) do { _Pragma("unroll") for (int m = 0; m < 4; ++m) _Pragma("unroll") for (int k = 0; k < 2; ++k) dst[m][k] = *(const LAS bf16x8*)(lds + PG8_SA(b, h) + aoff + m * 2048 + k * 1024); } while (0)
; #define PG8_LDB(dst, b, h) do { _Pragma("unroll") for (int n = 0; n < 2; ++n) _Pragma("unroll") for (int k = 0; k < 2; ++k) dst[n][k] = *(const LAS bf16x8*)(lds + PG8_SB(b, h) + boff + n * 2048 + k * 1024); } while (0)
; #define PG8_MMA(ai, bj, At, Bt) do { __builtin_amdgcn_s_setprio(1); _Pragma("unroll") for (int m = 0; m < 4; ++m) _Pragma("unroll") for (int n = 0; n < 2; ++n) _Pragma("unroll") for (int k = 0; k < 2; ++k) \
;         acc[ai][bj][m][n] = __builtin_amdgcn_mfma_f32_16x16x32_bf16(Bt[n][k], At[m][k], acc[ai][bj][m][n], 0, 0, 0); __builtin_amdgcn_s_setprio(0); } while (0)
; #define PG8_WAIT_V(n) asm volatile("s_waitcnt vmcnt(" #n ")" ::: "memory")
; #define PG8_WAIT_L(n) asm volatile("s_waitcnt lgkmcnt(" #n ")" ::: "memory")
; #define PG8_BAR __builtin_amdgcn_s_barrier()
; #define PG8_SCHED __builtin_amdgcn_sched_barrier(0)
; template <class Epi, bool PERM = true, bool DBLK = false>
; __device__ __forceinline__ void gemm_phase(LAS unsigned char* lds, const Gemm g, const StaticOrder& S, const Epi& E, const int tid) {
;     ...
;             const char* a1 = cA + (size_t)(t + 1) * kstep;
;             const char* a2 = last ? nA : (lastp ? cA : cA + (size_t)(t + 2) * kstep); const char* b2 = last ? nB : (lastp ? cB : cB + (size_t)(t + 2) * kstep);
;             const char* a3 = a2 + kstep; const char* b3 = b2 + kstep;
;             PG8_LDB(B0, 0, 0); PG8_LDB(B1, 0, 1); PG8_SCHED; PG8_LDA(At, 0, 0); PG8_STAGE(PG8_SA(1, 1), a1 + hstep, voffA);
;             PG8_WAIT_V(8); PG8_WAIT_L(0); PG8_BAR; PG8_MMA(0, 0, At, B0); PG8_MMA(0, 1, At, B1); PG8_BAR; PG8_SCHED;
;             PG8_LDA(At, 0, 1); PG8_STAGE(PG8_SB(0, 0), b2, voffB); PG8_STAGE(PG8_SB(0, 1), b2 + hstep, voffB); PG8_STAGE(PG8_SA(0, 0), a2, voffA);
;             PG8_WAIT_V(8); PG8_WAIT_L(0); PG8_BAR; PG8_MMA(1, 0, At, B0); PG8_MMA(1, 1, At, B1); PG8_BAR; PG8_SCHED;
.LBB0_212:
	s_add_u32 s34, s74, 0xfffc0080
	s_addc_u32 s35, s75, -1
	s_add_i32 s80, 0, 0x10000
	s_cmp_eq_u32 s83, 12
	s_cselect_b32 vcc_hi, s5, s35
	s_cselect_b32 vcc_lo, s29, s34
	s_cselect_b32 s35, s31, s82
	s_cselect_b32 s34, s55, s92
	s_add_i32 s64, 0, 0x14000
	v_add_u32_e32 v142, s80, v163
	v_add_u32_e32 v162, s64, v163
	ds_read_b128 v[130:133], v142
	ds_read_b128 v[134:137], v142 offset:1024
	ds_read_b128 v[138:141], v142 offset:2048
	ds_read_b128 v[142:145], v142 offset:3072
	ds_read_b128 v[158:161], v162
	ds_read_b128 v[166:169], v162 offset:1024
	ds_read_b128 v[170:173], v162 offset:2048
	ds_read_b128 v[174:177], v162 offset:3072
	s_add_i32 m0, s21, 0xc000
	ds_read_b128 v[178:181], v165
	ds_read_b128 v[182:185], v165 offset:1024
	ds_read_b128 v[186:189], v165 offset:2048
	ds_read_b128 v[190:193], v165 offset:3072
	ds_read_b128 v[202:205], v165 offset:4096
	ds_read_b128 v[206:209], v165 offset:5120
	ds_read_b128 v[210:213], v165 offset:6144
	ds_read_b128 v[214:217], v165 offset:7168
	global_load_lds_dwordx4 v154, s[74:75]
	s_add_i32 m0, s21, 0xe000
	s_nop 0
	global_load_lds_dwordx4 v152, s[74:75]
	s_waitcnt vmcnt(8)
	s_waitcnt lgkmcnt(0)
	s_barrier
	s_setprio 1
	s_waitcnt lgkmcnt(0)
	v_mfma_f32_16x16x32_bf16 v[126:129], v[130:133], v[178:181], v[126:129]
	v_mfma_f32_16x16x32_bf16 v[122:125], v[138:141], v[178:181], v[122:125]
	v_mfma_f32_16x16x32_bf16 v[118:121], v[130:133], v[186:189], v[118:121]
	v_mfma_f32_16x16x32_bf16 v[110:113], v[138:141], v[186:189], v[110:113]
	v_mfma_f32_16x16x32_bf16 v[102:105], v[130:133], v[202:205], v[102:105]
	v_mfma_f32_16x16x32_bf16 v[94:97], v[138:141], v[202:205], v[94:97]
	v_mfma_f32_16x16x32_bf16 v[86:89], v[130:133], v[210:213], v[86:89]
	v_mfma_f32_16x16x32_bf16 v[78:81], v[138:141], v[210:213], v[78:81]
	v_mfma_f32_16x16x32_bf16 v[126:129], v[134:137], v[182:185], v[126:129]
	v_mfma_f32_16x16x32_bf16 v[122:125], v[142:145], v[182:185], v[122:125]
	v_mfma_f32_16x16x32_bf16 v[118:121], v[134:137], v[190:193], v[118:121]
	v_mfma_f32_16x16x32_bf16 v[110:113], v[142:145], v[190:193], v[110:113]
	v_mfma_f32_16x16x32_bf16 v[102:105], v[134:137], v[206:209], v[102:105]
	v_mfma_f32_16x16x32_bf16 v[94:97], v[142:145], v[206:209], v[94:97]
	v_mfma_f32_16x16x32_bf16 v[86:89], v[134:137], v[214:217], v[86:89]
	v_mfma_f32_16x16x32_bf16 v[78:81], v[142:145], v[214:217], v[78:81]
	s_setprio 0
	s_setprio 1
	v_mfma_f32_16x16x32_bf16 v[114:117], v[158:161], v[178:181], v[114:117]
	v_mfma_f32_16x16x32_bf16 v[106:109], v[170:173], v[178:181], v[106:109]
	v_mfma_f32_16x16x32_bf16 v[98:101], v[158:161], v[186:189], v[98:101]
	v_mfma_f32_16x16x32_bf16 v[90:93], v[170:173], v[186:189], v[90:93]
	v_mfma_f32_16x16x32_bf16 v[82:85], v[158:161], v[202:205], v[82:85]
	v_mfma_f32_16x16x32_bf16 v[74:77], v[170:173], v[202:205], v[74:77]
	v_mfma_f32_16x16x32_bf16 v[70:73], v[158:161], v[210:213], v[70:73]
	v_mfma_f32_16x16x32_bf16 v[66:69], v[170:173], v[210:213], v[66:69]
	v_mfma_f32_16x16x32_bf16 v[114:117], v[166:169], v[182:185], v[114:117]
	v_mfma_f32_16x16x32_bf16 v[106:109], v[174:177], v[182:185], v[106:109]
	v_mfma_f32_16x16x32_bf16 v[98:101], v[166:169], v[190:193], v[98:101]
	v_mfma_f32_16x16x32_bf16 v[90:93], v[174:177], v[190:193], v[90:93]
	v_mfma_f32_16x16x32_bf16 v[82:85], v[166:169], v[206:209], v[82:85]
	v_mfma_f32_16x16x32_bf16 v[74:77], v[174:177], v[206:209], v[74:77]
	v_mfma_f32_16x16x32_bf16 v[70:73], v[166:169], v[214:217], v[70:73]
	v_mfma_f32_16x16x32_bf16 v[66:69], v[174:177], v[214:217], v[66:69]
	s_setprio 0
	s_barrier
	s_add_i32 s80, s80, s20
	s_mov_b32 m0, s80
	ds_read_b128 v[178:181], v165 offset:16384
	ds_read_b128 v[182:185], v165 offset:17408
	ds_read_b128 v[186:189], v165 offset:18432
	ds_read_b128 v[190:193], v165 offset:19456
	ds_read_b128 v[202:205], v165 offset:20480
	ds_read_b128 v[206:209], v165 offset:21504
	ds_read_b128 v[210:213], v165 offset:22528
	ds_read_b128 v[214:217], v165 offset:23552
	global_load_lds_dwordx4 v0, s[34:35]
	s_add_i32 m0, s80, 0x2000
	s_add_u32 s80, s34, 0x40000
	s_addc_u32 s81, s35, 0
	s_add_i32 s64, s64, s20
	global_load_lds_dwordx4 v150, s[34:35]
	s_mov_b32 m0, s64
	s_nop 0
	global_load_lds_dwordx4 v0, s[80:81]
	s_add_i32 m0, s64, 0x2000
	s_nop 0
	global_load_lds_dwordx4 v150, s[80:81]
	s_mov_b32 m0, s21
	s_nop 0
	global_load_lds_dwordx4 v146, vcc
	s_mov_b32 m0, s56
	s_nop 0
	global_load_lds_dwordx4 v148, vcc
	s_waitcnt vmcnt(8)
	s_waitcnt lgkmcnt(0)
	s_barrier
	s_setprio 1
	s_waitcnt lgkmcnt(0)
	v_mfma_f32_16x16x32_bf16 v[62:65], v[130:133], v[178:181], v[62:65]
	v_mfma_f32_16x16x32_bf16 v[58:61], v[138:141], v[178:181], v[58:61]
	v_mfma_f32_16x16x32_bf16 v[54:57], v[130:133], v[186:189], v[54:57]
	v_mfma_f32_16x16x32_bf16 v[46:49], v[138:141], v[186:189], v[46:49]
	v_mfma_f32_16x16x32_bf16 v[38:41], v[130:133], v[202:205], v[38:41]
	v_mfma_f32_16x16x32_bf16 v[30:33], v[138:141], v[202:205], v[30:33]
	v_mfma_f32_16x16x32_bf16 v[22:25], v[130:133], v[210:213], v[22:25]
	v_mfma_f32_16x16x32_bf16 v[14:17], v[138:141], v[210:213], v[14:17]
	v_mfma_f32_16x16x32_bf16 v[62:65], v[134:137], v[182:185], v[62:65]
	v_mfma_f32_16x16x32_bf16 v[58:61], v[142:145], v[182:185], v[58:61]
	v_mfma_f32_16x16x32_bf16 v[54:57], v[134:137], v[190:193], v[54:57]
	v_mfma_f32_16x16x32_bf16 v[46:49], v[142:145], v[190:193], v[46:49]
	v_mfma_f32_16x16x32_bf16 v[38:41], v[134:137], v[206:209], v[38:41]
	v_mfma_f32_16x16x32_bf16 v[30:33], v[142:145], v[206:209], v[30:33]
	v_mfma_f32_16x16x32_bf16 v[22:25], v[134:137], v[214:217], v[22:25]
	v_mfma_f32_16x16x32_bf16 v[14:17], v[142:145], v[214:217], v[14:17]
	s_setprio 0
	s_setprio 1
	v_mfma_f32_16x16x32_bf16 v[50:53], v[158:161], v[178:181], v[50:53]
	v_mfma_f32_16x16x32_bf16 v[42:45], v[170:173], v[178:181], v[42:45]
	v_mfma_f32_16x16x32_bf16 v[34:37], v[158:161], v[186:189], v[34:37]
	v_mfma_f32_16x16x32_bf16 v[26:29], v[170:173], v[186:189], v[26:29]
	v_mfma_f32_16x16x32_bf16 v[18:21], v[158:161], v[202:205], v[18:21]
	v_mfma_f32_16x16x32_bf16 v[10:13], v[170:173], v[202:205], v[10:13]
	v_mfma_f32_16x16x32_bf16 v[6:9], v[158:161], v[210:213], v[6:9]
	v_mfma_f32_16x16x32_bf16 v[2:5], v[170:173], v[210:213], v[2:5]
	v_mfma_f32_16x16x32_bf16 v[50:53], v[166:169], v[182:185], v[50:53]
	v_mfma_f32_16x16x32_bf16 v[42:45], v[174:177], v[182:185], v[42:45]
	v_mfma_f32_16x16x32_bf16 v[34:37], v[166:169], v[190:193], v[34:37]
	v_mfma_f32_16x16x32_bf16 v[26:29], v[174:177], v[190:193], v[26:29]
	v_mfma_f32_16x16x32_bf16 v[18:21], v[166:169], v[206:209], v[18:21]
	v_mfma_f32_16x16x32_bf16 v[10:13], v[174:177], v[206:209], v[10:13]
	v_mfma_f32_16x16x32_bf16 v[6:9], v[166:169], v[214:217], v[6:9]
	v_mfma_f32_16x16x32_bf16 v[2:5], v[174:177], v[214:217], v[2:5]
	s_setprio 0
	s_barrier
; #define PG8_STAGE(bufoff, gbase, voff) do { _Pragma("unroll") for (int _i = 0; _i < 2; ++_i) \
;         __builtin_amdgcn_global_load_lds((const unsigned*)((const char*)(gbase) + (voff)[_i]), (LAS unsigned*)(lds + (bufoff) + ldsw + _i * 8192), 16, 0, 0); } while (0)
; #define PG8_LDA(dst, b, h) do { _Pragma("unroll") for (int m = 0; m < 4; ++m) _Pragma("unroll") for (int k = 0; k < 2; ++k) dst[m][k] = *(const LAS bf16x8*)(lds + PG8_SA(b, h) + aoff + m * 2048 + k * 1024); } while (0)
; #define PG8_LDB(dst, b, h) do { _Pragma("unroll") for (int n = 0; n < 2; ++n) _Pragma("unroll") for (int k = 0; k < 2; ++k) dst[n][k] = *(const LAS bf16x8*)(lds + PG8_SB(b, h) + boff + n * 2048 + k * 1024); } while (0)
; #define PG8_MMA(ai, bj, At, Bt) do { __builtin_amdgcn_s_setprio(1); _Pragma("unroll") for (int m = 0; m < 4; ++m) _Pragma("unroll") for (int n = 0; n < 2; ++n) _Pragma("unroll") for (int k = 0; k < 2; ++k) \
;         acc[ai][bj][m][n] = __builtin_amdgcn_mfma_f32_16x16x32_bf16(Bt[n][k], At[m][k], acc[ai][bj][m][n], 0, 0, 0); __builtin_amdgcn_s_setprio(0); } while (0)
; #define PG8_WAIT_V(n) asm volatile("s_waitcnt vmcnt(" #n ")" ::: "memory")
; #define PG8_WAIT_L(n) asm volatile("s_waitcnt lgkmcnt(" #n ")" ::: "memory")
; #define PG8_BAR __builtin_amdgcn_s_barrier()
; #define PG8_SCHED __builtin_amdgcn_sched_barrier(0)
; template <class Epi, bool PERM = true, bool DBLK = false>
; __device__ __forceinline__ void gemm_phase(LAS unsigned char* lds, const Gemm g, const StaticOrder& S, const Epi& E, const int tid) {
;     ...
;             PG8_LDB(B0, 1, 0); PG8_LDB(B1, 1, 1); PG8_SCHED; PG8_LDA(At, 1, 0); PG8_STAGE(PG8_SA(0, 1), a2 + hstep, voffA);
;             PG8_WAIT_V(8); PG8_WAIT_L(0); PG8_BAR; PG8_MMA(0, 0, At, B0); PG8_MMA(0, 1, At, B1); PG8_BAR; PG8_SCHED;
;             PG8_LDA(At, 1, 1); PG8_STAGE(PG8_SB(1, 0), b3, voffB); PG8_STAGE(PG8_SB(1, 1), b3 + hstep, voffB); PG8_STAGE(PG8_SA(1, 0), a3, voffA);
;             PG8_WAIT_V(8); PG8_WAIT_L(0); PG8_BAR; PG8_MMA(1, 0, At, B0); PG8_MMA(1, 1, At, B1); PG8_BAR; PG8_SCHED;
;         }
	s_add_i32 s64, 0, 0x18000
	s_add_i32 s96, 0, 0x1c000
	v_add_u32_e32 v142, s64, v163
	v_add_u32_e32 v162, s96, v163
	ds_read_b128 v[130:133], v142
	ds_read_b128 v[134:137], v142 offset:1024
	ds_read_b128 v[138:141], v142 offset:2048
	ds_read_b128 v[142:145], v142 offset:3072
	ds_read_b128 v[158:161], v162
	ds_read_b128 v[166:169], v162 offset:1024
	ds_read_b128 v[170:173], v162 offset:2048
	ds_read_b128 v[174:177], v162 offset:3072
	s_add_u32 s80, vcc_lo, 0x40000
	s_addc_u32 s81, vcc_hi, 0
	s_mov_b32 m0, s57
	ds_read_b128 v[178:181], v165 offset:32768
	ds_read_b128 v[182:185], v165 offset:33792
	ds_read_b128 v[186:189], v165 offset:34816
	ds_read_b128 v[190:193], v165 offset:35840
	ds_read_b128 v[202:205], v165 offset:36864
	ds_read_b128 v[206:209], v165 offset:37888
	ds_read_b128 v[210:213], v165 offset:38912
	ds_read_b128 v[214:217], v165 offset:39936
	global_load_lds_dwordx4 v146, s[80:81]
	s_mov_b32 m0, s59
	s_nop 0
	global_load_lds_dwordx4 v148, s[80:81]
	s_waitcnt vmcnt(8)
	s_waitcnt lgkmcnt(0)
	s_barrier
	s_setprio 1
	s_waitcnt lgkmcnt(0)
	v_mfma_f32_16x16x32_bf16 v[126:129], v[130:133], v[178:181], v[126:129]
	v_mfma_f32_16x16x32_bf16 v[122:125], v[138:141], v[178:181], v[122:125]
	v_mfma_f32_16x16x32_bf16 v[118:121], v[130:133], v[186:189], v[118:121]
	v_mfma_f32_16x16x32_bf16 v[110:113], v[138:141], v[186:189], v[110:113]
	v_mfma_f32_16x16x32_bf16 v[102:105], v[130:133], v[202:205], v[102:105]
	v_mfma_f32_16x16x32_bf16 v[94:97], v[138:141], v[202:205], v[94:97]
	v_mfma_f32_16x16x32_bf16 v[86:89], v[130:133], v[210:213], v[86:89]
	v_mfma_f32_16x16x32_bf16 v[78:81], v[138:141], v[210:213], v[78:81]
	v_mfma_f32_16x16x32_bf16 v[126:129], v[134:137], v[182:185], v[126:129]
	v_mfma_f32_16x16x32_bf16 v[122:125], v[142:145], v[182:185], v[122:125]
	v_mfma_f32_16x16x32_bf16 v[118:121], v[134:137], v[190:193], v[118:121]
	v_mfma_f32_16x16x32_bf16 v[110:113], v[142:145], v[190:193], v[110:113]
	v_mfma_f32_16x16x32_bf16 v[102:105], v[134:137], v[206:209], v[102:105]
	v_mfma_f32_16x16x32_bf16 v[94:97], v[142:145], v[206:209], v[94:97]
	v_mfma_f32_16x16x32_bf16 v[86:89], v[134:137], v[214:217], v[86:89]
	v_mfma_f32_16x16x32_bf16 v[78:81], v[142:145], v[214:217], v[78:81]
	s_setprio 0
	s_setprio 1
	v_mfma_f32_16x16x32_bf16 v[114:117], v[158:161], v[178:181], v[114:117]
	v_mfma_f32_16x16x32_bf16 v[106:109], v[170:173], v[178:181], v[106:109]
	v_mfma_f32_16x16x32_bf16 v[98:101], v[158:161], v[186:189], v[98:101]
	v_mfma_f32_16x16x32_bf16 v[90:93], v[170:173], v[186:189], v[90:93]
	v_mfma_f32_16x16x32_bf16 v[82:85], v[158:161], v[202:205], v[82:85]
	v_mfma_f32_16x16x32_bf16 v[74:77], v[170:173], v[202:205], v[74:77]
	v_mfma_f32_16x16x32_bf16 v[70:73], v[158:161], v[210:213], v[70:73]
	v_mfma_f32_16x16x32_bf16 v[66:69], v[170:173], v[210:213], v[66:69]
	v_mfma_f32_16x16x32_bf16 v[114:117], v[166:169], v[182:185], v[114:117]
	v_mfma_f32_16x16x32_bf16 v[106:109], v[174:177], v[182:185], v[106:109]
	v_mfma_f32_16x16x32_bf16 v[98:101], v[166:169], v[190:193], v[98:101]
	v_mfma_f32_16x16x32_bf16 v[90:93], v[174:177], v[190:193], v[90:93]
	v_mfma_f32_16x16x32_bf16 v[82:85], v[166:169], v[206:209], v[82:85]
	v_mfma_f32_16x16x32_bf16 v[74:77], v[174:177], v[206:209], v[74:77]
	v_mfma_f32_16x16x32_bf16 v[70:73], v[166:169], v[214:217], v[70:73]
	v_mfma_f32_16x16x32_bf16 v[66:69], v[174:177], v[214:217], v[66:69]
	s_setprio 0
	s_barrier
	s_add_i32 s64, s64, s20
	s_add_u32 s98, s34, 0x80
	s_addc_u32 s99, s35, 0
	s_add_u32 s100, vcc_lo, 0x80
	s_addc_u32 s101, vcc_hi, 0
	s_mov_b32 m0, s64
	ds_read_b128 v[178:181], v165 offset:49152
	ds_read_b128 v[182:185], v165 offset:50176
	ds_read_b128 v[186:189], v165 offset:51200
	ds_read_b128 v[190:193], v165 offset:52224
	ds_read_b128 v[202:205], v165 offset:53248
	ds_read_b128 v[206:209], v165 offset:54272
	ds_read_b128 v[210:213], v165 offset:55296
	ds_read_b128 v[214:217], v165 offset:56320
	global_load_lds_dwordx4 v0, s[98:99]
	s_add_i32 m0, s64, 0x2000
	s_add_u32 s34, s34, 0x40080
	s_addc_u32 s35, s35, 0
	s_add_i32 s64, s96, s20
	global_load_lds_dwordx4 v150, s[98:99]
	s_mov_b32 m0, s64
	s_nop 0
	global_load_lds_dwordx4 v0, s[34:35]
	s_add_i32 m0, s64, 0x2000
	s_nop 0
	global_load_lds_dwordx4 v150, s[34:35]
	s_mov_b32 m0, s62
	s_nop 0
	global_load_lds_dwordx4 v146, s[100:101]
	s_mov_b32 m0, s63
	s_nop 0
	global_load_lds_dwordx4 v148, s[100:101]
	s_waitcnt vmcnt(8)
	s_waitcnt lgkmcnt(0)
	s_barrier
	s_setprio 1
	s_waitcnt lgkmcnt(0)
	v_mfma_f32_16x16x32_bf16 v[62:65], v[130:133], v[178:181], v[62:65]
	v_mfma_f32_16x16x32_bf16 v[58:61], v[138:141], v[178:181], v[58:61]
	v_mfma_f32_16x16x32_bf16 v[54:57], v[130:133], v[186:189], v[54:57]
	v_mfma_f32_16x16x32_bf16 v[46:49], v[138:141], v[186:189], v[46:49]
	v_mfma_f32_16x16x32_bf16 v[38:41], v[130:133], v[202:205], v[38:41]
	v_mfma_f32_16x16x32_bf16 v[30:33], v[138:141], v[202:205], v[30:33]
	v_mfma_f32_16x16x32_bf16 v[22:25], v[130:133], v[210:213], v[22:25]
	v_mfma_f32_16x16x32_bf16 v[14:17], v[138:141], v[210:213], v[14:17]
	v_mfma_f32_16x16x32_bf16 v[62:65], v[134:137], v[182:185], v[62:65]
	v_mfma_f32_16x16x32_bf16 v[58:61], v[142:145], v[182:185], v[58:61]
	v_mfma_f32_16x16x32_bf16 v[54:57], v[134:137], v[190:193], v[54:57]
	v_mfma_f32_16x16x32_bf16 v[46:49], v[142:145], v[190:193], v[46:49]
	v_mfma_f32_16x16x32_bf16 v[38:41], v[134:137], v[206:209], v[38:41]
	v_mfma_f32_16x16x32_bf16 v[30:33], v[142:145], v[206:209], v[30:33]
	v_mfma_f32_16x16x32_bf16 v[22:25], v[134:137], v[214:217], v[22:25]
	v_mfma_f32_16x16x32_bf16 v[14:17], v[142:145], v[214:217], v[14:17]
	s_setprio 0
	s_setprio 1
	v_mfma_f32_16x16x32_bf16 v[50:53], v[158:161], v[178:181], v[50:53]
	v_mfma_f32_16x16x32_bf16 v[42:45], v[170:173], v[178:181], v[42:45]
	v_mfma_f32_16x16x32_bf16 v[34:37], v[158:161], v[186:189], v[34:37]
	v_mfma_f32_16x16x32_bf16 v[26:29], v[170:173], v[186:189], v[26:29]
	v_mfma_f32_16x16x32_bf16 v[18:21], v[158:161], v[202:205], v[18:21]
	v_mfma_f32_16x16x32_bf16 v[10:13], v[170:173], v[202:205], v[10:13]
	v_mfma_f32_16x16x32_bf16 v[6:9], v[158:161], v[210:213], v[6:9]
	v_mfma_f32_16x16x32_bf16 v[2:5], v[170:173], v[210:213], v[2:5]
	v_mfma_f32_16x16x32_bf16 v[50:53], v[166:169], v[182:185], v[50:53]
	v_mfma_f32_16x16x32_bf16 v[42:45], v[174:177], v[182:185], v[42:45]
	v_mfma_f32_16x16x32_bf16 v[34:37], v[166:169], v[190:193], v[34:37]
	v_mfma_f32_16x16x32_bf16 v[26:29], v[174:177], v[190:193], v[26:29]
	v_mfma_f32_16x16x32_bf16 v[18:21], v[166:169], v[206:209], v[18:21]
	v_mfma_f32_16x16x32_bf16 v[10:13], v[174:177], v[206:209], v[10:13]
	v_mfma_f32_16x16x32_bf16 v[6:9], v[166:169], v[214:217], v[6:9]
	v_mfma_f32_16x16x32_bf16 v[2:5], v[174:177], v[214:217], v[2:5]
	s_setprio 0
	s_barrier
	s_add_i32 s83, s83, 2
	s_add_u32 s92, s92, 0x100
	s_addc_u32 s82, s82, 0
	s_add_u32 s74, s74, 0x100
	s_addc_u32 s75, s75, 0
	s_cmp_gt_u32 s83, 13
	s_cbranch_scc0 .LBB0_212
	s_and_b64 vcc, exec, s[26:27]
	s_cbranch_vccz .LBB0_215
	s_barrier

; #define PG8_STAGE(bufoff, gbase, voff) do { _Pragma("unroll") for (int _i = 0; _i < 2; ++_i) \
;         __builtin_amdgcn_global_load_lds((const unsigned*)((const char*)(gbase) + (voff)[_i]), (LAS unsigned*)(lds + (bufoff) + ldsw + _i * 8192), 16, 0, 0); } while (0)
; #define PG8_WAIT_V(n) asm volatile("s_waitcnt vmcnt(" #n ")" ::: "memory")
; #define PG8_BAR __builtin_amdgcn_s_barrier()
; template <class Epi, bool PERM = true, bool DBLK = false>
; __device__ __forceinline__ void gemm_phase(LAS unsigned char* lds, const Gemm g, const StaticOrder& S, const Epi& E, const int tid) {
;     ...
;     for (int i = 0; i < 2; ++i) { int R, C; stage_rc(tid * 16 + i * 8192, R, C); const int Rb = PERM ? ((R & ~31) + perm32(R & 31)) : R;
;         voffA[i] = (unsigned)(R * K + C) * 2u; voffB[i] = (unsigned)(Rb * K + C) * 2u; }
;     const size_t kstep = (size_t)(BK * 2);
;     const size_t hstep = (size_t)HALF * K * 2;
;     const size_t tstep = 2 * hstep;
;     const unsigned ldsw = (unsigned)wid * 1024u;
;     const int aoff = lds_byte(wr * 64 + fr, fq * 8), boff = lds_byte(wc * 32 + fr, fq * 8);
;     ...
;     Unit cur, nxt; int ui = 0;
;     if (!S.next(0, cur)) return;
;     f32x4 acc[2][2][4][2];
; #pragma unroll
;     for (int a = 0; a < 2; ++a)
; #pragma unroll
;         for (int b = 0; b < 2; ++b)
; #pragma unroll
;             for (int m = 0; m < 4; ++m)
; #pragma unroll
;                 for (int n = 0; n < 2; ++n) acc[a][b][m][n] = (f32x4){0.f, 0.f, 0.f, 0.f};
;     bf16x8 At[4][2], B0[2][2], B1[2][2];
;     const char* cA = (const char*)g.A + (size_t)cur.pm * tstep; const char* cB = (const char*)g.Bt + (size_t)cur.pn * tstep;
;     PG8_STAGE(PG8_SB(0, 0), cB, voffB); PG8_STAGE(PG8_SB(0, 1), cB + hstep, voffB); PG8_STAGE(PG8_SA(0, 0), cA, voffA); PG8_STAGE(PG8_SA(0, 1), cA + hstep, voffA);
;     if (wr == 1) PG8_BAR;
;     PG8_WAIT_V(2); PG8_BAR;
;     PG8_STAGE(PG8_SB(1, 0), cB + kstep, voffB); PG8_STAGE(PG8_SA(1, 0), cA + kstep, voffA); PG8_STAGE(PG8_SB(1, 1), cB + hstep + kstep, voffB);
;     PG8_WAIT_V(6); PG8_BAR;
.LBB0_290:
	s_lshl_b32 s1, s1, 5
	v_and_b32_e32 v3, 48, v2
	v_lshlrev_b32_e32 v12, 6, v2
	s_movk_i32 s9, 0x3c0
	v_lshlrev_b32_e32 v2, 2, v2
	s_and_b32 s55, s1, 0x60
	v_lshl_add_u64 v[4:5], s[28:29], 0, v[0:1]
	v_mov_b32_e32 v131, v1
	s_lshl_b32 s54, s8, 6
	s_lshl_b32 s8, s8, 13
	v_and_or_b32 v3, v12, s9, v3
	v_and_b32_e32 v2, 32, v2
	s_lshl_b32 s1, s55, 7
	v_lshl_add_u64 v[6:7], s[28:29], 0, v[130:131]
	v_mov_b32_e32 v135, v1
	v_bitop3_b32 v12, v3, s8, v2 bitop3:0xde
	v_bitop3_b32 v136, s1, v3, v2 bitop3:0xf6
	s_add_i32 m0, s35, 0x18000
	v_lshl_add_u64 v[2:3], v[4:5], 0, s[84:85]
	v_lshl_add_u64 v[8:9], s[22:23], 0, v[134:135]
	v_mov_b32_e32 v133, v1
	s_waitcnt vmcnt(2)
	s_barrier
	global_load_lds_dwordx4 v[2:3], off
	v_lshl_add_u64 v[2:3], v[6:7], 0, s[84:85]
	s_add_i32 m0, s35, 0x1a000
	s_add_i32 s56, s35, 0x8000
	s_add_i32 s57, s35, 0xa000
	v_lshl_add_u64 v[10:11], s[22:23], 0, v[132:133]
	global_load_lds_dwordx4 v[2:3], off
	v_lshl_add_u64 v[2:3], v[8:9], 0, s[84:85]
	s_mov_b32 m0, s56
	s_add_u32 s8, s28, 0x10080
	global_load_lds_dwordx4 v[2:3], off
	v_lshl_add_u64 v[2:3], v[10:11], 0, s[84:85]
	s_mov_b32 m0, s57
	s_addc_u32 s9, s29, 0
	global_load_lds_dwordx4 v[2:3], off
	s_add_i32 m0, s35, 0x1c000
	s_nop 0
	global_load_lds_dwordx4 v0, s[8:9]
	v_lshl_add_u64 v[2:3], s[8:9], 0, v[130:131]
	s_add_i32 m0, s35, 0x1e000
	s_cmpk_lt_u32 s0, 0x100
	global_load_lds_dwordx4 v[2:3], off
	v_readlane_b32 s0, v255, 12
	s_waitcnt vmcnt(6)
	v_readlane_b32 s1, v255, 13
	v_readlane_b32 s10, v255, 38
	s_mov_b32 s63, s0
	v_readlane_b32 s0, v255, 8
	s_cselect_b64 s[8:9], -1, 0
	v_add_u32_e32 v137, 0, v12
	v_readlane_b32 s11, v255, 39
	v_readlane_b32 s59, v255, 35
	s_mov_b32 s62, s0
	s_barrier
	v_readlane_b32 s1, v255, 9
	s_branch .LBB0_293

; #define PG8_STAGE(bufoff, gbase, voff) do { _Pragma("unroll") for (int _i = 0; _i < 2; ++_i) \
;         __builtin_amdgcn_global_load_lds((const unsigned*)((const char*)(gbase) + (voff)[_i]), (LAS unsigned*)(lds + (bufoff) + ldsw + _i * 8192), 16, 0, 0); } while (0)
; #define PG8_LDA(dst, b, h) do { _Pragma("unroll") for (int m = 0; m < 4; ++m) _Pragma("unroll") for (int k = 0; k < 2; ++k) dst[m][k] = *(const LAS bf16x8*)(lds + PG8_SA(b, h) + aoff + m * 2048 + k * 1024); } while (0)
; #define PG8_LDB(dst, b, h) do { _Pragma("unroll") for (int n = 0; n < 2; ++n) _Pragma("unroll") for (int k = 0; k < 2; ++k) dst[n][k] = *(const LAS bf16x8*)(lds + PG8_SB(b, h) + boff + n * 2048 + k * 1024); } while (0)
; #define PG8_WAIT_V(n) asm volatile("s_waitcnt vmcnt(" #n ")" ::: "memory")
; #define PG8_WAIT_L(n) asm volatile("s_waitcnt lgkmcnt(" #n ")" ::: "memory")
; #define PG8_BAR __builtin_amdgcn_s_barrier()
; template <class Epi, bool PERM = true, bool DBLK = false>
; __device__ __forceinline__ void gemm_phase(LAS unsigned char* lds, const Gemm g, const StaticOrder& S, const Epi& E, const int tid) {
;     ...
;         const bool has_next = S.next(ui + 1, nxt);
;         const char* nA = has_next ? (const char*)g.A + (size_t)nxt.pm * tstep : cA; const char* nB = has_next ? (const char*)g.Bt + (size_t)nxt.pn * tstep : cB;
;         for (int t2 = 0; t2 < (DBLK ? 2 * nt : nt); t2 += 2) {
;             const int t = DBLK ? (t2 >= nt ? t2 - nt : t2) : t2;
;             const bool lastp = (t == nt - 2);
;             const bool last = DBLK ? (t2 == 2 * nt - 2) : lastp;
;             const char* a1 = cA + (size_t)(t + 1) * kstep;
;             const char* a2 = last ? nA : (lastp ? cA : cA + (size_t)(t + 2) * kstep); const char* b2 = last ? nB : (lastp ? cB : cB + (size_t)(t + 2) * kstep);
;             const char* a3 = a2 + kstep; const char* b3 = b2 + kstep;
;             PG8_LDB(B0, 0, 0); PG8_LDB(B1, 0, 1); PG8_SCHED; PG8_LDA(At, 0, 0); PG8_STAGE(PG8_SA(1, 1), a1 + hstep, voffA);
;             PG8_WAIT_V(8); PG8_WAIT_L(0); PG8_BAR; PG8_MMA(0, 0, At, B0); PG8_MMA(0, 1, At, B1); PG8_BAR; PG8_SCHED;
;             PG8_LDA(At, 0, 1); PG8_STAGE(PG8_SB(0, 0), b2, voffB); PG8_STAGE(PG8_SB(0, 1), b2 + hstep, voffB); PG8_STAGE(PG8_SA(0, 0), a2, voffA);
;             PG8_WAIT_V(8); PG8_WAIT_L(0); PG8_BAR; PG8_MMA(1, 0, At, B0); PG8_MMA(1, 1, At, B1); PG8_BAR; PG8_SCHED;
.LBB0_298:
	s_ashr_i32 s15, s14, 31
	s_lshl_b64 s[16:17], s[14:15], 17
	s_add_u32 s16, s2, s16
	s_addc_u32 s17, s3, s17
	s_and_b64 s[18:19], s[0:1], exec
	s_cselect_b32 s31, s17, s23
	s_cselect_b32 s30, s16, s22
	s_ashr_i32 s13, s12, 31
	s_lshl_b64 s[18:19], s[12:13], 17
	s_add_u32 s18, s20, s18
	s_addc_u32 s19, s21, s19
	s_and_b64 s[26:27], s[0:1], exec
	s_cselect_b32 s27, s19, s29
	s_cselect_b32 s26, s18, s28
	s_add_i32 s72, 0, 0x10000
	s_add_i32 s64, 0, 0x14000
	v_add_u32_e32 v212, s72, v136
	v_add_u32_e32 v213, s64, v136
	ds_read_b128 v[2:5], v212
	ds_read_b128 v[6:9], v212 offset:1024
	ds_read_b128 v[10:13], v212 offset:2048
	ds_read_b128 v[14:17], v212 offset:3072
	s_waitcnt vmcnt(0)
	ds_read_b128 v[18:21], v213
	ds_read_b128 v[22:25], v213 offset:1024
	ds_read_b128 v[26:29], v213 offset:2048
	ds_read_b128 v[30:33], v213 offset:3072
	s_add_u32 s66, s22, 0x10080
	s_addc_u32 s67, s23, 0
	s_add_i32 s74, s35, 0xc000
	v_lshl_add_u64 v[66:67], s[66:67], 0, v[134:135]
	s_mov_b32 m0, s74
	s_add_i32 s13, s35, 0xe000
	ds_read_b128 v[34:37], v137
	ds_read_b128 v[38:41], v137 offset:1024
	ds_read_b128 v[42:45], v137 offset:2048
	ds_read_b128 v[46:49], v137 offset:3072
	ds_read_b128 v[50:53], v137 offset:4096
	ds_read_b128 v[54:57], v137 offset:5120
	ds_read_b128 v[58:61], v137 offset:6144
	ds_read_b128 v[62:65], v137 offset:7168
	global_load_lds_dwordx4 v[66:67], off
	v_lshl_add_u64 v[66:67], s[66:67], 0, v[132:133]
	s_mov_b32 m0, s13
	s_nop 0
	global_load_lds_dwordx4 v[66:67], off
	s_waitcnt vmcnt(8)
	s_waitcnt lgkmcnt(0)
	s_barrier
	s_setprio 1
	s_waitcnt lgkmcnt(0)
	v_mfma_f32_16x16x32_bf16 v[66:69], v[2:5], v[34:37], 0
	v_mfma_f32_16x16x32_bf16 v[70:73], v[10:13], v[34:37], 0
	v_mfma_f32_16x16x32_bf16 v[74:77], v[2:5], v[42:45], 0
	v_mfma_f32_16x16x32_bf16 v[78:81], v[10:13], v[42:45], 0
	v_mfma_f32_16x16x32_bf16 v[82:85], v[2:5], v[50:53], 0
	v_mfma_f32_16x16x32_bf16 v[86:89], v[10:13], v[50:53], 0
	v_mfma_f32_16x16x32_bf16 v[90:93], v[2:5], v[58:61], 0
	v_mfma_f32_16x16x32_bf16 v[94:97], v[10:13], v[58:61], 0
	v_mfma_f32_16x16x32_bf16 v[66:69], v[6:9], v[38:41], v[66:69]
	v_mfma_f32_16x16x32_bf16 v[70:73], v[14:17], v[38:41], v[70:73]
	v_mfma_f32_16x16x32_bf16 v[74:77], v[6:9], v[46:49], v[74:77]
	v_mfma_f32_16x16x32_bf16 v[78:81], v[14:17], v[46:49], v[78:81]
	v_mfma_f32_16x16x32_bf16 v[82:85], v[6:9], v[54:57], v[82:85]
	v_mfma_f32_16x16x32_bf16 v[86:89], v[14:17], v[54:57], v[86:89]
	v_mfma_f32_16x16x32_bf16 v[90:93], v[6:9], v[62:65], v[90:93]
	v_mfma_f32_16x16x32_bf16 v[94:97], v[14:17], v[62:65], v[94:97]
	s_setprio 0
	s_setprio 1
	v_mfma_f32_16x16x32_bf16 v[98:101], v[18:21], v[34:37], 0
	v_mfma_f32_16x16x32_bf16 v[34:37], v[26:29], v[34:37], 0
	v_mfma_f32_16x16x32_bf16 v[98:101], v[22:25], v[38:41], v[98:101]
	v_mfma_f32_16x16x32_bf16 v[34:37], v[30:33], v[38:41], v[34:37]
	v_mfma_f32_16x16x32_bf16 v[38:41], v[18:21], v[42:45], 0
	v_mfma_f32_16x16x32_bf16 v[42:45], v[26:29], v[42:45], 0
	v_mfma_f32_16x16x32_bf16 v[38:41], v[22:25], v[46:49], v[38:41]
	v_mfma_f32_16x16x32_bf16 v[42:45], v[30:33], v[46:49], v[42:45]
	v_mfma_f32_16x16x32_bf16 v[46:49], v[18:21], v[50:53], 0
	v_mfma_f32_16x16x32_bf16 v[50:53], v[26:29], v[50:53], 0
	v_mfma_f32_16x16x32_bf16 v[46:49], v[22:25], v[54:57], v[46:49]
	v_mfma_f32_16x16x32_bf16 v[50:53], v[30:33], v[54:57], v[50:53]
	v_mfma_f32_16x16x32_bf16 v[54:57], v[18:21], v[58:61], 0
	v_mfma_f32_16x16x32_bf16 v[58:61], v[26:29], v[58:61], 0
	v_mfma_f32_16x16x32_bf16 v[54:57], v[22:25], v[62:65], v[54:57]
	v_mfma_f32_16x16x32_bf16 v[58:61], v[30:33], v[62:65], v[58:61]
	s_setprio 0
	s_barrier
	s_add_i32 s72, s72, s34
	v_lshl_add_u64 v[194:195], s[28:29], 0, v[0:1]
	s_mov_b64 s[82:83], 0x100
	s_add_i32 s15, s72, 0x2000
	v_lshl_add_u64 v[138:139], v[194:195], 0, s[82:83]
	s_mov_b32 m0, s72
	v_lshl_add_u64 v[196:197], s[28:29], 0, v[130:131]
	s_add_u32 s78, s28, 0x10100
	ds_read_b128 v[62:65], v137 offset:16384
	ds_read_b128 v[102:105], v137 offset:17408
	ds_read_b128 v[106:109], v137 offset:18432
	ds_read_b128 v[110:113], v137 offset:19456
	ds_read_b128 v[114:117], v137 offset:20480
	ds_read_b128 v[118:121], v137 offset:21504
	ds_read_b128 v[122:125], v137 offset:22528
	ds_read_b128 v[126:129], v137 offset:23552
	global_load_lds_dwordx4 v[138:139], off
	v_lshl_add_u64 v[138:139], v[196:197], 0, s[82:83]
	s_mov_b32 m0, s15
	s_addc_u32 s79, s29, 0
	s_add_i32 s66, s64, s34
	global_load_lds_dwordx4 v[138:139], off
	s_mov_b32 m0, s66
	s_add_i32 s67, s66, 0x2000
	global_load_lds_dwordx4 v0, s[78:79]
	s_mov_b32 m0, s67
	v_lshl_add_u64 v[198:199], s[22:23], 0, v[134:135]
	global_load_lds_dwordx4 v130, s[78:79]
	v_lshl_add_u64 v[138:139], v[198:199], 0, s[82:83]
	s_mov_b32 m0, s35
	v_lshl_add_u64 v[200:201], s[22:23], 0, v[132:133]
	global_load_lds_dwordx4 v[138:139], off
	v_lshl_add_u64 v[138:139], v[200:201], 0, s[82:83]
	s_mov_b32 m0, s36
	s_nop 0
	global_load_lds_dwordx4 v[138:139], off
	s_waitcnt vmcnt(8)
	s_waitcnt lgkmcnt(0)
	s_barrier
; #define PG8_STAGE(bufoff, gbase, voff) do { _Pragma("unroll") for (int _i = 0; _i < 2; ++_i) \
;         __builtin_amdgcn_global_load_lds((const unsigned*)((const char*)(gbase) + (voff)[_i]), (LAS unsigned*)(lds + (bufoff) + ldsw + _i * 8192), 16, 0, 0); } while (0)
; #define PG8_LDA(dst, b, h) do { _Pragma("unroll") for (int m = 0; m < 4; ++m) _Pragma("unroll") for (int k = 0; k < 2; ++k) dst[m][k] = *(const LAS bf16x8*)(lds + PG8_SA(b, h) + aoff + m * 2048 + k * 1024); } while (0)
; #define PG8_LDB(dst, b, h) do { _Pragma("unroll") for (int n = 0; n < 2; ++n) _Pragma("unroll") for (int k = 0; k < 2; ++k) dst[n][k] = *(const LAS bf16x8*)(lds + PG8_SB(b, h) + boff + n * 2048 + k * 1024); } while (0)
; #define PG8_MMA(ai, bj, At, Bt) do { __builtin_amdgcn_s_setprio(1); _Pragma("unroll") for (int m = 0; m < 4; ++m) _Pragma("unroll") for (int n = 0; n < 2; ++n) _Pragma("unroll") for (int k = 0; k < 2; ++k) \
;         acc[ai][bj][m][n] = __builtin_amdgcn_mfma_f32_16x16x32_bf16(Bt[n][k], At[m][k], acc[ai][bj][m][n], 0, 0, 0); __builtin_amdgcn_s_setprio(0); } while (0)
; #define PG8_WAIT_V(n) asm volatile("s_waitcnt vmcnt(" #n ")" ::: "memory")
; #define PG8_WAIT_L(n) asm volatile("s_waitcnt lgkmcnt(" #n ")" ::: "memory")
; #define PG8_BAR __builtin_amdgcn_s_barrier()
; #define PG8_SCHED __builtin_amdgcn_sched_barrier(0)
; template <class Epi, bool PERM = true, bool DBLK = false>
; __device__ __forceinline__ void gemm_phase(LAS unsigned char* lds, const Gemm g, const StaticOrder& S, const Epi& E, const int tid) {
;     ...
;             PG8_WAIT_V(8); PG8_WAIT_L(0); PG8_BAR; PG8_MMA(1, 0, At, B0); PG8_MMA(1, 1, At, B1); PG8_BAR; PG8_SCHED;
;             PG8_LDB(B0, 1, 0); PG8_LDB(B1, 1, 1); PG8_SCHED; PG8_LDA(At, 1, 0); PG8_STAGE(PG8_SA(0, 1), a2 + hstep, voffA);
;             PG8_WAIT_V(8); PG8_WAIT_L(0); PG8_BAR; PG8_MMA(0, 0, At, B0); PG8_MMA(0, 1, At, B1); PG8_BAR; PG8_SCHED;
	s_setprio 1
	s_waitcnt lgkmcnt(0)
	v_mfma_f32_16x16x32_bf16 v[138:141], v[2:5], v[62:65], 0
	v_mfma_f32_16x16x32_bf16 v[146:149], v[2:5], v[106:109], 0
	v_mfma_f32_16x16x32_bf16 v[154:157], v[2:5], v[114:117], 0
	v_mfma_f32_16x16x32_bf16 v[2:5], v[2:5], v[122:125], 0
	v_mfma_f32_16x16x32_bf16 v[138:141], v[6:9], v[102:105], v[138:141]
	v_mfma_f32_16x16x32_bf16 v[146:149], v[6:9], v[110:113], v[146:149]
	v_mfma_f32_16x16x32_bf16 v[154:157], v[6:9], v[118:121], v[154:157]
	v_mfma_f32_16x16x32_bf16 v[2:5], v[6:9], v[126:129], v[2:5]
	v_mfma_f32_16x16x32_bf16 v[6:9], v[10:13], v[122:125], 0
	v_mfma_f32_16x16x32_bf16 v[142:145], v[10:13], v[62:65], 0
	v_mfma_f32_16x16x32_bf16 v[150:153], v[10:13], v[106:109], 0
	v_mfma_f32_16x16x32_bf16 v[158:161], v[10:13], v[114:117], 0
	v_mfma_f32_16x16x32_bf16 v[6:9], v[14:17], v[126:129], v[6:9]
	v_mfma_f32_16x16x32_bf16 v[142:145], v[14:17], v[102:105], v[142:145]
	v_mfma_f32_16x16x32_bf16 v[150:153], v[14:17], v[110:113], v[150:153]
	v_mfma_f32_16x16x32_bf16 v[158:161], v[14:17], v[118:121], v[158:161]
	s_setprio 0
	s_setprio 1
	v_mfma_f32_16x16x32_bf16 v[10:13], v[18:21], v[62:65], 0
	v_mfma_f32_16x16x32_bf16 v[14:17], v[26:29], v[62:65], 0
	v_mfma_f32_16x16x32_bf16 v[10:13], v[22:25], v[102:105], v[10:13]
	v_mfma_f32_16x16x32_bf16 v[14:17], v[30:33], v[102:105], v[14:17]
	v_mfma_f32_16x16x32_bf16 v[62:65], v[18:21], v[106:109], 0
	v_mfma_f32_16x16x32_bf16 v[102:105], v[26:29], v[106:109], 0
	v_mfma_f32_16x16x32_bf16 v[106:109], v[18:21], v[114:117], 0
	v_mfma_f32_16x16x32_bf16 v[18:21], v[18:21], v[122:125], 0
	v_mfma_f32_16x16x32_bf16 v[62:65], v[22:25], v[110:113], v[62:65]
	v_mfma_f32_16x16x32_bf16 v[102:105], v[30:33], v[110:113], v[102:105]
	v_mfma_f32_16x16x32_bf16 v[106:109], v[22:25], v[118:121], v[106:109]
	v_mfma_f32_16x16x32_bf16 v[110:113], v[26:29], v[114:117], 0
	v_mfma_f32_16x16x32_bf16 v[18:21], v[22:25], v[126:129], v[18:21]
	v_mfma_f32_16x16x32_bf16 v[22:25], v[26:29], v[122:125], 0
	v_mfma_f32_16x16x32_bf16 v[110:113], v[30:33], v[118:121], v[110:113]
	v_mfma_f32_16x16x32_bf16 v[22:25], v[30:33], v[126:129], v[22:25]
	s_setprio 0
	s_barrier
	s_add_i32 s75, 0, 0x18000
	s_add_i32 s64, 0, 0x1c000
	v_add_u32_e32 v218, s75, v136
	v_add_u32_e32 v226, s64, v136
	ds_read_b128 v[26:29], v218
	ds_read_b128 v[30:33], v218 offset:1024
	ds_read_b128 v[114:117], v218 offset:2048
	ds_read_b128 v[118:121], v218 offset:3072
	ds_read_b128 v[122:125], v226
	ds_read_b128 v[126:129], v226 offset:1024
	ds_read_b128 v[162:165], v226 offset:2048
	ds_read_b128 v[166:169], v226 offset:3072
	s_add_u32 s78, s22, 0x10100
	s_addc_u32 s79, s23, 0
	s_mov_b32 m0, s52
	v_lshl_add_u64 v[210:211], s[78:79], 0, v[134:135]
	ds_read_b128 v[170:173], v137 offset:32768
	ds_read_b128 v[174:177], v137 offset:33792
	ds_read_b128 v[178:181], v137 offset:34816
	ds_read_b128 v[182:185], v137 offset:35840
	ds_read_b128 v[186:189], v137 offset:36864
	ds_read_b128 v[190:193], v137 offset:37888
	ds_read_b128 v[202:205], v137 offset:38912
	ds_read_b128 v[206:209], v137 offset:39936
	global_load_lds_dwordx4 v[210:211], off
	s_mov_b32 m0, s53
	s_nop 0
	global_load_lds_dwordx4 v132, s[78:79]
	s_waitcnt vmcnt(8)
	s_waitcnt lgkmcnt(0)
	s_barrier
	s_setprio 1
	s_waitcnt lgkmcnt(0)
	v_mfma_f32_16x16x32_bf16 v[66:69], v[26:29], v[170:173], v[66:69]
	v_mfma_f32_16x16x32_bf16 v[70:73], v[114:117], v[170:173], v[70:73]
	v_mfma_f32_16x16x32_bf16 v[74:77], v[26:29], v[178:181], v[74:77]
	v_mfma_f32_16x16x32_bf16 v[78:81], v[114:117], v[178:181], v[78:81]
	v_mfma_f32_16x16x32_bf16 v[82:85], v[26:29], v[186:189], v[82:85]
	v_mfma_f32_16x16x32_bf16 v[86:89], v[114:117], v[186:189], v[86:89]
	v_mfma_f32_16x16x32_bf16 v[90:93], v[26:29], v[202:205], v[90:93]
	v_mfma_f32_16x16x32_bf16 v[94:97], v[114:117], v[202:205], v[94:97]
	v_mfma_f32_16x16x32_bf16 v[66:69], v[30:33], v[174:177], v[66:69]
	v_mfma_f32_16x16x32_bf16 v[70:73], v[118:121], v[174:177], v[70:73]
	v_mfma_f32_16x16x32_bf16 v[74:77], v[30:33], v[182:185], v[74:77]
	v_mfma_f32_16x16x32_bf16 v[78:81], v[118:121], v[182:185], v[78:81]
	v_mfma_f32_16x16x32_bf16 v[82:85], v[30:33], v[190:193], v[82:85]
	v_mfma_f32_16x16x32_bf16 v[86:89], v[118:121], v[190:193], v[86:89]
	v_mfma_f32_16x16x32_bf16 v[90:93], v[30:33], v[206:209], v[90:93]
	v_mfma_f32_16x16x32_bf16 v[94:97], v[118:121], v[206:209], v[94:97]
	s_setprio 0
	s_setprio 1
	v_mfma_f32_16x16x32_bf16 v[98:101], v[122:125], v[170:173], v[98:101]
	v_mfma_f32_16x16x32_bf16 v[34:37], v[162:165], v[170:173], v[34:37]
	v_mfma_f32_16x16x32_bf16 v[38:41], v[122:125], v[178:181], v[38:41]
	v_mfma_f32_16x16x32_bf16 v[42:45], v[162:165], v[178:181], v[42:45]
	v_mfma_f32_16x16x32_bf16 v[46:49], v[122:125], v[186:189], v[46:49]
	v_mfma_f32_16x16x32_bf16 v[50:53], v[162:165], v[186:189], v[50:53]
	v_mfma_f32_16x16x32_bf16 v[54:57], v[122:125], v[202:205], v[54:57]
	v_mfma_f32_16x16x32_bf16 v[58:61], v[162:165], v[202:205], v[58:61]
	v_mfma_f32_16x16x32_bf16 v[98:101], v[126:129], v[174:177], v[98:101]
	v_mfma_f32_16x16x32_bf16 v[34:37], v[166:169], v[174:177], v[34:37]
	v_mfma_f32_16x16x32_bf16 v[38:41], v[126:129], v[182:185], v[38:41]
	v_mfma_f32_16x16x32_bf16 v[42:45], v[166:169], v[182:185], v[42:45]
	v_mfma_f32_16x16x32_bf16 v[46:49], v[126:129], v[190:193], v[46:49]
	v_mfma_f32_16x16x32_bf16 v[50:53], v[166:169], v[190:193], v[50:53]
	v_mfma_f32_16x16x32_bf16 v[54:57], v[126:129], v[206:209], v[54:57]
	v_mfma_f32_16x16x32_bf16 v[58:61], v[166:169], v[206:209], v[58:61]
	s_setprio 0
	s_barrier
; #define PG8_STAGE(bufoff, gbase, voff) do { _Pragma("unroll") for (int _i = 0; _i < 2; ++_i) \
;         __builtin_amdgcn_global_load_lds((const unsigned*)((const char*)(gbase) + (voff)[_i]), (LAS unsigned*)(lds + (bufoff) + ldsw + _i * 8192), 16, 0, 0); } while (0)
; #define PG8_LDA(dst, b, h) do { _Pragma("unroll") for (int m = 0; m < 4; ++m) _Pragma("unroll") for (int k = 0; k < 2; ++k) dst[m][k] = *(const LAS bf16x8*)(lds + PG8_SA(b, h) + aoff + m * 2048 + k * 1024); } while (0)
; #define PG8_LDB(dst, b, h) do { _Pragma("unroll") for (int n = 0; n < 2; ++n) _Pragma("unroll") for (int k = 0; k < 2; ++k) dst[n][k] = *(const LAS bf16x8*)(lds + PG8_SB(b, h) + boff + n * 2048 + k * 1024); } while (0)
; #define PG8_MMA(ai, bj, At, Bt) do { __builtin_amdgcn_s_setprio(1); _Pragma("unroll") for (int m = 0; m < 4; ++m) _Pragma("unroll") for (int n = 0; n < 2; ++n) _Pragma("unroll") for (int k = 0; k < 2; ++k) \
;         acc[ai][bj][m][n] = __builtin_amdgcn_mfma_f32_16x16x32_bf16(Bt[n][k], At[m][k], acc[ai][bj][m][n], 0, 0, 0); __builtin_amdgcn_s_setprio(0); } while (0)
; #define PG8_WAIT_V(n) asm volatile("s_waitcnt vmcnt(" #n ")" ::: "memory")
; template <class Epi, bool PERM = true, bool DBLK = false>
; __device__ __forceinline__ void gemm_phase(LAS unsigned char* lds, const Gemm g, const StaticOrder& S, const Epi& E, const int tid) {
;     ...
;             PG8_LDB(B0, 0, 0); PG8_LDB(B1, 0, 1); PG8_SCHED; PG8_LDA(At, 0, 0); PG8_STAGE(PG8_SA(1, 1), a1 + hstep, voffA);
;             PG8_WAIT_V(8); PG8_WAIT_L(0); PG8_BAR; PG8_MMA(0, 0, At, B0); PG8_MMA(0, 1, At, B1); PG8_BAR; PG8_SCHED;
;             PG8_LDA(At, 0, 1); PG8_STAGE(PG8_SB(0, 0), b2, voffB); PG8_STAGE(PG8_SB(0, 1), b2 + hstep, voffB); PG8_STAGE(PG8_SA(0, 0), a2, voffA);
;             PG8_WAIT_V(8); PG8_WAIT_L(0); PG8_BAR; PG8_MMA(1, 0, At, B0); PG8_MMA(1, 1, At, B1); PG8_BAR; PG8_SCHED;
;             PG8_LDB(B0, 1, 0); PG8_LDB(B1, 1, 1); PG8_SCHED; PG8_LDA(At, 1, 0); PG8_STAGE(PG8_SA(0, 1), a2 + hstep, voffA);
;             PG8_WAIT_V(8); PG8_WAIT_L(0); PG8_BAR; PG8_MMA(0, 0, At, B0); PG8_MMA(0, 1, At, B1); PG8_BAR; PG8_SCHED;
;             PG8_LDA(At, 1, 1); PG8_STAGE(PG8_SB(1, 0), b3, voffB); PG8_STAGE(PG8_SB(1, 1), b3 + hstep, voffB); PG8_STAGE(PG8_SA(1, 0), a3, voffA);
;             PG8_WAIT_V(8); PG8_WAIT_L(0); PG8_BAR; PG8_MMA(1, 0, At, B0); PG8_MMA(1, 1, At, B1); PG8_BAR; PG8_SCHED;
;         }
	s_add_i32 s75, s75, s34
	s_mov_b64 s[82:83], 0x180
	s_add_i32 s73, s75, 0x2000
	v_lshl_add_u64 v[194:195], v[194:195], 0, s[82:83]
	s_mov_b32 m0, s75
	s_add_u32 s78, s28, 0x10180
	ds_read_b128 v[170:173], v137 offset:49152
	ds_read_b128 v[174:177], v137 offset:50176
	ds_read_b128 v[178:181], v137 offset:51200
	ds_read_b128 v[182:185], v137 offset:52224
	ds_read_b128 v[186:189], v137 offset:53248
	ds_read_b128 v[190:193], v137 offset:54272
	ds_read_b128 v[202:205], v137 offset:55296
	ds_read_b128 v[206:209], v137 offset:56320
	global_load_lds_dwordx4 v[194:195], off
	v_lshl_add_u64 v[194:195], v[196:197], 0, s[82:83]
	s_mov_b32 m0, s73
	s_addc_u32 s79, s29, 0
	s_add_i32 s28, s64, s34
	global_load_lds_dwordx4 v[194:195], off
	s_mov_b32 m0, s28
	s_add_i32 s29, s28, 0x2000
	global_load_lds_dwordx4 v0, s[78:79]
	s_mov_b32 m0, s29
	s_nop 0
	global_load_lds_dwordx4 v130, s[78:79]
	v_lshl_add_u64 v[194:195], v[198:199], 0, s[82:83]
	s_mov_b32 m0, s56
	s_nop 0
	global_load_lds_dwordx4 v[194:195], off
	v_lshl_add_u64 v[194:195], v[200:201], 0, s[82:83]
	s_mov_b32 m0, s57
	s_nop 0
	global_load_lds_dwordx4 v[194:195], off
	s_waitcnt vmcnt(8)
	s_waitcnt lgkmcnt(0)
	s_barrier
	s_setprio 1
	s_waitcnt lgkmcnt(0)
	v_mfma_f32_16x16x32_bf16 v[2:5], v[26:29], v[202:205], v[2:5]
	v_mfma_f32_16x16x32_bf16 v[6:9], v[114:117], v[202:205], v[6:9]
	v_mfma_f32_16x16x32_bf16 v[138:141], v[26:29], v[170:173], v[138:141]
	v_mfma_f32_16x16x32_bf16 v[142:145], v[114:117], v[170:173], v[142:145]
	v_mfma_f32_16x16x32_bf16 v[146:149], v[26:29], v[178:181], v[146:149]
	v_mfma_f32_16x16x32_bf16 v[150:153], v[114:117], v[178:181], v[150:153]
	v_mfma_f32_16x16x32_bf16 v[154:157], v[26:29], v[186:189], v[154:157]
	v_mfma_f32_16x16x32_bf16 v[158:161], v[114:117], v[186:189], v[158:161]
	v_mfma_f32_16x16x32_bf16 v[2:5], v[30:33], v[206:209], v[2:5]
	v_mfma_f32_16x16x32_bf16 v[6:9], v[118:121], v[206:209], v[6:9]
	v_mfma_f32_16x16x32_bf16 v[138:141], v[30:33], v[174:177], v[138:141]
	v_mfma_f32_16x16x32_bf16 v[142:145], v[118:121], v[174:177], v[142:145]
	v_mfma_f32_16x16x32_bf16 v[146:149], v[30:33], v[182:185], v[146:149]
	v_mfma_f32_16x16x32_bf16 v[150:153], v[118:121], v[182:185], v[150:153]
	v_mfma_f32_16x16x32_bf16 v[154:157], v[30:33], v[190:193], v[154:157]
	v_mfma_f32_16x16x32_bf16 v[158:161], v[118:121], v[190:193], v[158:161]
	s_setprio 0
	s_setprio 1
	v_mfma_f32_16x16x32_bf16 v[10:13], v[122:125], v[170:173], v[10:13]
	v_mfma_f32_16x16x32_bf16 v[14:17], v[162:165], v[170:173], v[14:17]
	v_mfma_f32_16x16x32_bf16 v[26:29], v[122:125], v[178:181], v[62:65]
	v_mfma_f32_16x16x32_bf16 v[30:33], v[162:165], v[178:181], v[102:105]
	v_mfma_f32_16x16x32_bf16 v[62:65], v[122:125], v[186:189], v[106:109]
	v_mfma_f32_16x16x32_bf16 v[102:105], v[162:165], v[186:189], v[110:113]
	v_mfma_f32_16x16x32_bf16 v[18:21], v[122:125], v[202:205], v[18:21]
	v_mfma_f32_16x16x32_bf16 v[22:25], v[162:165], v[202:205], v[22:25]
	v_mfma_f32_16x16x32_bf16 v[10:13], v[126:129], v[174:177], v[10:13]
	v_mfma_f32_16x16x32_bf16 v[14:17], v[166:169], v[174:177], v[14:17]
	v_mfma_f32_16x16x32_bf16 v[26:29], v[126:129], v[182:185], v[26:29]
	v_mfma_f32_16x16x32_bf16 v[30:33], v[166:169], v[182:185], v[30:33]
	v_mfma_f32_16x16x32_bf16 v[62:65], v[126:129], v[190:193], v[62:65]
	v_mfma_f32_16x16x32_bf16 v[102:105], v[166:169], v[190:193], v[102:105]
	v_mfma_f32_16x16x32_bf16 v[18:21], v[126:129], v[206:209], v[18:21]
	v_mfma_f32_16x16x32_bf16 v[22:25], v[166:169], v[206:209], v[22:25]
	s_setprio 0
	s_barrier
	ds_read_b128 v[106:109], v212
	ds_read_b128 v[110:113], v212 offset:1024
	ds_read_b128 v[114:117], v212 offset:2048
	ds_read_b128 v[118:121], v212 offset:3072
	ds_read_b128 v[122:125], v213
	ds_read_b128 v[126:129], v213 offset:1024
	ds_read_b128 v[162:165], v213 offset:2048
	ds_read_b128 v[166:169], v213 offset:3072
	s_add_u32 s22, s22, 0x10180
	s_addc_u32 s23, s23, 0
	s_mov_b32 m0, s74
	v_lshl_add_u64 v[194:195], s[22:23], 0, v[134:135]
	ds_read_b128 v[170:173], v137
	ds_read_b128 v[174:177], v137 offset:1024
	ds_read_b128 v[178:181], v137 offset:2048
	ds_read_b128 v[182:185], v137 offset:3072
	ds_read_b128 v[186:189], v137 offset:4096
	ds_read_b128 v[190:193], v137 offset:5120
	ds_read_b128 v[202:205], v137 offset:6144
	ds_read_b128 v[206:209], v137 offset:7168
	global_load_lds_dwordx4 v[194:195], off
	s_mov_b32 m0, s13
	s_nop 0
	global_load_lds_dwordx4 v132, s[22:23]
	s_waitcnt vmcnt(8)
	s_waitcnt lgkmcnt(0)
	s_barrier
	s_setprio 1
	s_waitcnt lgkmcnt(0)
	v_mfma_f32_16x16x32_bf16 v[66:69], v[106:109], v[170:173], v[66:69]
	v_mfma_f32_16x16x32_bf16 v[70:73], v[114:117], v[170:173], v[70:73]
	v_mfma_f32_16x16x32_bf16 v[74:77], v[106:109], v[178:181], v[74:77]
	v_mfma_f32_16x16x32_bf16 v[78:81], v[114:117], v[178:181], v[78:81]
	v_mfma_f32_16x16x32_bf16 v[82:85], v[106:109], v[186:189], v[82:85]
	v_mfma_f32_16x16x32_bf16 v[86:89], v[114:117], v[186:189], v[86:89]
	v_mfma_f32_16x16x32_bf16 v[90:93], v[106:109], v[202:205], v[90:93]
	v_mfma_f32_16x16x32_bf16 v[66:69], v[110:113], v[174:177], v[66:69]
	v_mfma_f32_16x16x32_bf16 v[70:73], v[118:121], v[174:177], v[70:73]
	v_mfma_f32_16x16x32_bf16 v[74:77], v[110:113], v[182:185], v[74:77]
	v_mfma_f32_16x16x32_bf16 v[78:81], v[118:121], v[182:185], v[78:81]
	v_mfma_f32_16x16x32_bf16 v[82:85], v[110:113], v[190:193], v[82:85]
	v_mfma_f32_16x16x32_bf16 v[86:89], v[118:121], v[190:193], v[86:89]
	v_mfma_f32_16x16x32_bf16 v[210:213], v[110:113], v[206:209], v[90:93]
	v_mfma_f32_16x16x32_bf16 v[90:93], v[114:117], v[202:205], v[94:97]
	v_mfma_f32_16x16x32_bf16 v[214:217], v[118:121], v[206:209], v[90:93]
	s_setprio 0
	s_setprio 1
	v_mfma_f32_16x16x32_bf16 v[90:93], v[122:125], v[170:173], v[98:101]
	v_mfma_f32_16x16x32_bf16 v[34:37], v[162:165], v[170:173], v[34:37]
	v_mfma_f32_16x16x32_bf16 v[38:41], v[122:125], v[178:181], v[38:41]
	v_mfma_f32_16x16x32_bf16 v[42:45], v[162:165], v[178:181], v[42:45]
	v_mfma_f32_16x16x32_bf16 v[46:49], v[122:125], v[186:189], v[46:49]
	v_mfma_f32_16x16x32_bf16 v[50:53], v[162:165], v[186:189], v[50:53]
	v_mfma_f32_16x16x32_bf16 v[54:57], v[122:125], v[202:205], v[54:57]
	v_mfma_f32_16x16x32_bf16 v[98:101], v[126:129], v[174:177], v[90:93]
	v_mfma_f32_16x16x32_bf16 v[34:37], v[166:169], v[174:177], v[34:37]
	v_mfma_f32_16x16x32_bf16 v[38:41], v[126:129], v[182:185], v[38:41]
	v_mfma_f32_16x16x32_bf16 v[42:45], v[166:169], v[182:185], v[42:45]
	v_mfma_f32_16x16x32_bf16 v[46:49], v[126:129], v[190:193], v[46:49]
	v_mfma_f32_16x16x32_bf16 v[50:53], v[166:169], v[190:193], v[50:53]
	v_mfma_f32_16x16x32_bf16 v[54:57], v[126:129], v[206:209], v[54:57]
	v_mfma_f32_16x16x32_bf16 v[58:61], v[162:165], v[202:205], v[58:61]
	v_mfma_f32_16x16x32_bf16 v[170:173], v[166:169], v[206:209], v[58:61]
	s_setprio 0
	s_barrier
; #define PG8_STAGE(bufoff, gbase, voff) do { _Pragma("unroll") for (int _i = 0; _i < 2; ++_i) \
;         __builtin_amdgcn_global_load_lds((const unsigned*)((const char*)(gbase) + (voff)[_i]), (LAS unsigned*)(lds + (bufoff) + ldsw + _i * 8192), 16, 0, 0); } while (0)
; #define PG8_LDA(dst, b, h) do { _Pragma("unroll") for (int m = 0; m < 4; ++m) _Pragma("unroll") for (int k = 0; k < 2; ++k) dst[m][k] = *(const LAS bf16x8*)(lds + PG8_SA(b, h) + aoff + m * 2048 + k * 1024); } while (0)
; #define PG8_LDB(dst, b, h) do { _Pragma("unroll") for (int n = 0; n < 2; ++n) _Pragma("unroll") for (int k = 0; k < 2; ++k) dst[n][k] = *(const LAS bf16x8*)(lds + PG8_SB(b, h) + boff + n * 2048 + k * 1024); } while (0)
; #define PG8_MMA(ai, bj, At, Bt) do { __builtin_amdgcn_s_setprio(1); _Pragma("unroll") for (int m = 0; m < 4; ++m) _Pragma("unroll") for (int n = 0; n < 2; ++n) _Pragma("unroll") for (int k = 0; k < 2; ++k) \
;         acc[ai][bj][m][n] = __builtin_amdgcn_mfma_f32_16x16x32_bf16(Bt[n][k], At[m][k], acc[ai][bj][m][n], 0, 0, 0); __builtin_amdgcn_s_setprio(0); } while (0)
; #define PG8_WAIT_V(n) asm volatile("s_waitcnt vmcnt(" #n ")" ::: "memory")
; #define PG8_WAIT_L(n) asm volatile("s_waitcnt lgkmcnt(" #n ")" ::: "memory")
; #define PG8_BAR __builtin_amdgcn_s_barrier()
; #define PG8_SCHED __builtin_amdgcn_sched_barrier(0)
; template <class Epi, bool PERM = true, bool DBLK = false>
; __device__ __forceinline__ void gemm_phase(LAS unsigned char* lds, const Gemm g, const StaticOrder& S, const Epi& E, const int tid) {
;     ...
;             PG8_LDA(At, 0, 1); PG8_STAGE(PG8_SB(0, 0), b2, voffB); PG8_STAGE(PG8_SB(0, 1), b2 + hstep, voffB); PG8_STAGE(PG8_SA(0, 0), a2, voffA);
;             PG8_WAIT_V(8); PG8_WAIT_L(0); PG8_BAR; PG8_MMA(1, 0, At, B0); PG8_MMA(1, 1, At, B1); PG8_BAR; PG8_SCHED;
;             PG8_LDB(B0, 1, 0); PG8_LDB(B1, 1, 1); PG8_SCHED; PG8_LDA(At, 1, 0); PG8_STAGE(PG8_SA(0, 1), a2 + hstep, voffA);
;             PG8_WAIT_V(8); PG8_WAIT_L(0); PG8_BAR; PG8_MMA(0, 0, At, B0); PG8_MMA(0, 1, At, B1); PG8_BAR; PG8_SCHED;
	s_mov_b32 m0, s72
	v_lshl_add_u64 v[252:253], s[26:27], 0, v[0:1]
	s_add_u32 s22, s26, 0x10000
	s_nop 1
	ds_read_b128 v[58:61], v137 offset:16384
	ds_read_b128 v[90:93], v137 offset:17408
	ds_read_b128 v[94:97], v137 offset:18432
	ds_read_b128 v[174:177], v137 offset:19456
	ds_read_b128 v[178:181], v137 offset:20480
	ds_read_b128 v[182:185], v137 offset:21504
	ds_read_b128 v[186:189], v137 offset:22528
	ds_read_b128 v[190:193], v137 offset:23552
	global_load_lds_dwordx4 v[252:253], off
	v_lshl_add_u64 v[232:233], s[26:27], 0, v[130:131]
	s_mov_b32 m0, s15
	s_addc_u32 s23, s27, 0
	global_load_lds_dwordx4 v[232:233], off
	s_mov_b32 m0, s66
	v_lshl_add_u64 v[230:231], s[30:31], 0, v[134:135]
	global_load_lds_dwordx4 v0, s[22:23]
	s_mov_b32 m0, s67
	v_lshl_add_u64 v[234:235], s[30:31], 0, v[132:133]
	global_load_lds_dwordx4 v130, s[22:23]
	s_mov_b32 m0, s35
	s_nop 0
	global_load_lds_dwordx4 v[230:231], off
	s_mov_b32 m0, s36
	s_nop 0
	global_load_lds_dwordx4 v[234:235], off
	s_waitcnt vmcnt(8)
	s_waitcnt lgkmcnt(0)
	s_barrier
	s_setprio 1
	s_waitcnt lgkmcnt(0)
	v_mfma_f32_16x16x32_bf16 v[2:5], v[106:109], v[186:189], v[2:5]
	v_mfma_f32_16x16x32_bf16 v[6:9], v[114:117], v[186:189], v[6:9]
	v_mfma_f32_16x16x32_bf16 v[138:141], v[106:109], v[58:61], v[138:141]
	v_mfma_f32_16x16x32_bf16 v[142:145], v[114:117], v[58:61], v[142:145]
	v_mfma_f32_16x16x32_bf16 v[146:149], v[106:109], v[94:97], v[146:149]
	v_mfma_f32_16x16x32_bf16 v[150:153], v[114:117], v[94:97], v[150:153]
	v_mfma_f32_16x16x32_bf16 v[154:157], v[106:109], v[178:181], v[154:157]
	v_mfma_f32_16x16x32_bf16 v[158:161], v[114:117], v[178:181], v[158:161]
	v_mfma_f32_16x16x32_bf16 v[2:5], v[110:113], v[190:193], v[2:5]
	v_mfma_f32_16x16x32_bf16 v[6:9], v[118:121], v[190:193], v[6:9]
	v_mfma_f32_16x16x32_bf16 v[138:141], v[110:113], v[90:93], v[138:141]
	v_mfma_f32_16x16x32_bf16 v[142:145], v[118:121], v[90:93], v[142:145]
	v_mfma_f32_16x16x32_bf16 v[146:149], v[110:113], v[174:177], v[146:149]
	v_mfma_f32_16x16x32_bf16 v[150:153], v[118:121], v[174:177], v[150:153]
	v_mfma_f32_16x16x32_bf16 v[154:157], v[110:113], v[182:185], v[154:157]
	v_mfma_f32_16x16x32_bf16 v[158:161], v[118:121], v[182:185], v[158:161]
	s_setprio 0
	s_setprio 1
	v_mfma_f32_16x16x32_bf16 v[26:29], v[122:125], v[94:97], v[26:29]
	v_mfma_f32_16x16x32_bf16 v[202:205], v[126:129], v[174:177], v[26:29]
	v_mfma_f32_16x16x32_bf16 v[26:29], v[162:165], v[94:97], v[30:33]
	v_mfma_f32_16x16x32_bf16 v[174:177], v[166:169], v[174:177], v[26:29]
	v_mfma_f32_16x16x32_bf16 v[26:29], v[122:125], v[178:181], v[62:65]
	v_mfma_f32_16x16x32_bf16 v[10:13], v[122:125], v[58:61], v[10:13]
	v_mfma_f32_16x16x32_bf16 v[14:17], v[162:165], v[58:61], v[14:17]
	v_mfma_f32_16x16x32_bf16 v[206:209], v[126:129], v[182:185], v[26:29]
	v_mfma_f32_16x16x32_bf16 v[26:29], v[162:165], v[178:181], v[102:105]
	v_mfma_f32_16x16x32_bf16 v[18:21], v[122:125], v[186:189], v[18:21]
	v_mfma_f32_16x16x32_bf16 v[10:13], v[126:129], v[90:93], v[10:13]
	v_mfma_f32_16x16x32_bf16 v[14:17], v[166:169], v[90:93], v[14:17]
	v_mfma_f32_16x16x32_bf16 v[178:181], v[166:169], v[182:185], v[26:29]
	v_mfma_f32_16x16x32_bf16 v[182:185], v[126:129], v[190:193], v[18:21]
	v_mfma_f32_16x16x32_bf16 v[18:21], v[162:165], v[186:189], v[22:25]
	v_mfma_f32_16x16x32_bf16 v[162:165], v[166:169], v[190:193], v[18:21]
	s_setprio 0
	s_barrier
	ds_read_b128 v[102:105], v218
	ds_read_b128 v[166:169], v218 offset:1024
	ds_read_b128 v[186:189], v218 offset:2048
	ds_read_b128 v[190:193], v218 offset:3072
	ds_read_b128 v[218:221], v226
	ds_read_b128 v[222:225], v226 offset:1024
	ds_read_b128 v[236:239], v226 offset:2048
	ds_read_b128 v[240:243], v226 offset:3072
	s_add_u32 s22, s30, 0x10000
	s_addc_u32 s23, s31, 0
	s_mov_b32 m0, s52
	v_lshl_add_u64 v[26:27], s[22:23], 0, v[134:135]
	ds_read_b128 v[18:21], v137 offset:32768
	ds_read_b128 v[22:25], v137 offset:33792
	ds_read_b128 v[110:113], v137 offset:34816
	ds_read_b128 v[244:247], v137 offset:35840
	ds_read_b128 v[248:251], v137 offset:36864
	ds_read_b128 v[226:229], v137 offset:37888
	ds_read_b128 v[194:197], v137 offset:38912
	ds_read_b128 v[198:201], v137 offset:39936
	global_load_lds_dwordx4 v[26:27], off
	v_lshl_add_u64 v[26:27], s[22:23], 0, v[132:133]
	s_mov_b32 m0, s53
	s_nop 0
	global_load_lds_dwordx4 v[26:27], off
	s_waitcnt vmcnt(8)
	s_waitcnt lgkmcnt(0)
	s_barrier
; #define PG8_STAGE(bufoff, gbase, voff) do { _Pragma("unroll") for (int _i = 0; _i < 2; ++_i) \
;         __builtin_amdgcn_global_load_lds((const unsigned*)((const char*)(gbase) + (voff)[_i]), (LAS unsigned*)(lds + (bufoff) + ldsw + _i * 8192), 16, 0, 0); } while (0)
; #define PG8_LDA(dst, b, h) do { _Pragma("unroll") for (int m = 0; m < 4; ++m) _Pragma("unroll") for (int k = 0; k < 2; ++k) dst[m][k] = *(const LAS bf16x8*)(lds + PG8_SA(b, h) + aoff + m * 2048 + k * 1024); } while (0)
; #define PG8_MMA(ai, bj, At, Bt) do { __builtin_amdgcn_s_setprio(1); _Pragma("unroll") for (int m = 0; m < 4; ++m) _Pragma("unroll") for (int n = 0; n < 2; ++n) _Pragma("unroll") for (int k = 0; k < 2; ++k) \
;         acc[ai][bj][m][n] = __builtin_amdgcn_mfma_f32_16x16x32_bf16(Bt[n][k], At[m][k], acc[ai][bj][m][n], 0, 0, 0); __builtin_amdgcn_s_setprio(0); } while (0)
; #define PG8_WAIT_V(n) asm volatile("s_waitcnt vmcnt(" #n ")" ::: "memory")
; #define PG8_WAIT_L(n) asm volatile("s_waitcnt lgkmcnt(" #n ")" ::: "memory")
; #define PG8_BAR __builtin_amdgcn_s_barrier()
; #define PG8_SCHED __builtin_amdgcn_sched_barrier(0)
; template <class Epi, bool PERM = true, bool DBLK = false>
; __device__ __forceinline__ void gemm_phase(LAS unsigned char* lds, const Gemm g, const StaticOrder& S, const Epi& E, const int tid) {
;     ...
;             PG8_WAIT_V(8); PG8_WAIT_L(0); PG8_BAR; PG8_MMA(0, 0, At, B0); PG8_MMA(0, 1, At, B1); PG8_BAR; PG8_SCHED;
;             PG8_LDA(At, 1, 1); PG8_STAGE(PG8_SB(1, 0), b3, voffB); PG8_STAGE(PG8_SB(1, 1), b3 + hstep, voffB); PG8_STAGE(PG8_SA(1, 0), a3, voffA);
;             PG8_WAIT_V(8); PG8_WAIT_L(0); PG8_BAR; PG8_MMA(1, 0, At, B0); PG8_MMA(1, 1, At, B1); PG8_BAR; PG8_SCHED;
;         }
;         if (wr == 0) PG8_BAR;
	s_setprio 1
	s_waitcnt lgkmcnt(0)
	v_mfma_f32_16x16x32_bf16 v[26:29], v[102:105], v[18:21], v[66:69]
	v_mfma_f32_16x16x32_bf16 v[114:117], v[166:169], v[22:25], v[26:29]
	v_mfma_f32_16x16x32_bf16 v[26:29], v[186:189], v[18:21], v[70:73]
	v_mfma_f32_16x16x32_bf16 v[118:121], v[190:193], v[22:25], v[26:29]
	v_mfma_f32_16x16x32_bf16 v[26:29], v[102:105], v[110:113], v[74:77]
	v_mfma_f32_16x16x32_bf16 v[90:93], v[166:169], v[244:247], v[26:29]
	v_mfma_f32_16x16x32_bf16 v[26:29], v[186:189], v[110:113], v[78:81]
	v_mfma_f32_16x16x32_bf16 v[94:97], v[190:193], v[244:247], v[26:29]
	v_mfma_f32_16x16x32_bf16 v[26:29], v[102:105], v[248:251], v[82:85]
	v_mfma_f32_16x16x32_bf16 v[58:61], v[166:169], v[226:229], v[26:29]
	v_mfma_f32_16x16x32_bf16 v[26:29], v[186:189], v[248:251], v[86:89]
	v_mfma_f32_16x16x32_bf16 v[62:65], v[190:193], v[226:229], v[26:29]
	v_mfma_f32_16x16x32_bf16 v[26:29], v[102:105], v[194:197], v[210:213]
	v_mfma_f32_16x16x32_bf16 v[30:33], v[186:189], v[194:197], v[214:217]
	v_mfma_f32_16x16x32_bf16 v[26:29], v[166:169], v[198:201], v[26:29]
	v_mfma_f32_16x16x32_bf16 v[30:33], v[190:193], v[198:201], v[30:33]
	s_setprio 0
	s_setprio 1
	v_mfma_f32_16x16x32_bf16 v[66:69], v[218:221], v[18:21], v[98:101]
	v_mfma_f32_16x16x32_bf16 v[18:21], v[236:239], v[18:21], v[34:37]
	v_mfma_f32_16x16x32_bf16 v[126:129], v[240:243], v[22:25], v[18:21]
	v_mfma_f32_16x16x32_bf16 v[18:21], v[218:221], v[110:113], v[38:41]
	v_mfma_f32_16x16x32_bf16 v[106:109], v[222:225], v[244:247], v[18:21]
	v_mfma_f32_16x16x32_bf16 v[18:21], v[236:239], v[110:113], v[42:45]
	v_mfma_f32_16x16x32_bf16 v[110:113], v[240:243], v[244:247], v[18:21]
	v_mfma_f32_16x16x32_bf16 v[18:21], v[218:221], v[248:251], v[46:49]
	v_mfma_f32_16x16x32_bf16 v[74:77], v[222:225], v[226:229], v[18:21]
	v_mfma_f32_16x16x32_bf16 v[18:21], v[236:239], v[248:251], v[50:53]
	v_mfma_f32_16x16x32_bf16 v[78:81], v[240:243], v[226:229], v[18:21]
	v_mfma_f32_16x16x32_bf16 v[18:21], v[218:221], v[194:197], v[54:57]
	v_mfma_f32_16x16x32_bf16 v[42:45], v[222:225], v[198:201], v[18:21]
	v_mfma_f32_16x16x32_bf16 v[18:21], v[236:239], v[194:197], v[170:173]
	v_mfma_f32_16x16x32_bf16 v[122:125], v[222:225], v[22:25], v[66:69]
	v_mfma_f32_16x16x32_bf16 v[46:49], v[240:243], v[198:201], v[18:21]
	s_setprio 0
	s_barrier
	s_mov_b32 m0, s75
	s_nop 2
	v_lshl_add_u64 v[18:19], v[252:253], 0, s[84:85]
	s_add_u32 s22, s26, 0x10080
	ds_read_b128 v[34:37], v137 offset:49152
	ds_read_b128 v[38:41], v137 offset:50176
	ds_read_b128 v[70:73], v137 offset:51200
	ds_read_b128 v[170:173], v137 offset:52224
	ds_read_b128 v[194:197], v137 offset:53248
	ds_read_b128 v[198:201], v137 offset:54272
	ds_read_b128 v[210:213], v137 offset:55296
	ds_read_b128 v[214:217], v137 offset:56320
	global_load_lds_dwordx4 v[18:19], off
	v_lshl_add_u64 v[18:19], v[232:233], 0, s[84:85]
	s_mov_b32 m0, s73
	s_addc_u32 s23, s27, 0
	global_load_lds_dwordx4 v[18:19], off
	s_mov_b32 m0, s28
	s_nop 0
	global_load_lds_dwordx4 v0, s[22:23]
	s_mov_b32 m0, s29
	s_nop 0
	global_load_lds_dwordx4 v130, s[22:23]
	v_lshl_add_u64 v[18:19], v[230:231], 0, s[84:85]
	s_mov_b32 m0, s56
	s_nop 0
	global_load_lds_dwordx4 v[18:19], off
	v_lshl_add_u64 v[18:19], v[234:235], 0, s[84:85]
	s_mov_b32 m0, s57
	s_nop 0
	global_load_lds_dwordx4 v[18:19], off
	s_waitcnt vmcnt(8)
	s_waitcnt lgkmcnt(0)
	s_barrier
	s_setprio 1
	s_waitcnt lgkmcnt(0)
	v_mfma_f32_16x16x32_bf16 v[18:21], v[102:105], v[34:37], v[138:141]
	v_mfma_f32_16x16x32_bf16 v[82:85], v[166:169], v[38:41], v[18:21]
	v_mfma_f32_16x16x32_bf16 v[18:21], v[186:189], v[34:37], v[142:145]
	v_mfma_f32_16x16x32_bf16 v[86:89], v[190:193], v[38:41], v[18:21]
	v_mfma_f32_16x16x32_bf16 v[18:21], v[102:105], v[70:73], v[146:149]
	v_mfma_f32_16x16x32_bf16 v[50:53], v[166:169], v[170:173], v[18:21]
	v_mfma_f32_16x16x32_bf16 v[18:21], v[186:189], v[70:73], v[150:153]
	v_mfma_f32_16x16x32_bf16 v[54:57], v[190:193], v[170:173], v[18:21]
	v_mfma_f32_16x16x32_bf16 v[18:21], v[102:105], v[194:197], v[154:157]
	v_mfma_f32_16x16x32_bf16 v[22:25], v[186:189], v[194:197], v[158:161]
	v_mfma_f32_16x16x32_bf16 v[2:5], v[102:105], v[210:213], v[2:5]
	v_mfma_f32_16x16x32_bf16 v[6:9], v[186:189], v[210:213], v[6:9]
	v_mfma_f32_16x16x32_bf16 v[18:21], v[166:169], v[198:201], v[18:21]
	v_mfma_f32_16x16x32_bf16 v[22:25], v[190:193], v[198:201], v[22:25]
	v_mfma_f32_16x16x32_bf16 v[2:5], v[166:169], v[214:217], v[2:5]
	v_mfma_f32_16x16x32_bf16 v[6:9], v[190:193], v[214:217], v[6:9]
	s_setprio 0
	s_setprio 1
	v_mfma_f32_16x16x32_bf16 v[10:13], v[218:221], v[34:37], v[10:13]
	v_mfma_f32_16x16x32_bf16 v[98:101], v[222:225], v[38:41], v[10:13]
	v_mfma_f32_16x16x32_bf16 v[10:13], v[236:239], v[34:37], v[14:17]
	v_mfma_f32_16x16x32_bf16 v[102:105], v[240:243], v[38:41], v[10:13]
	v_mfma_f32_16x16x32_bf16 v[10:13], v[218:221], v[70:73], v[202:205]
	v_mfma_f32_16x16x32_bf16 v[66:69], v[222:225], v[170:173], v[10:13]
	v_mfma_f32_16x16x32_bf16 v[10:13], v[236:239], v[70:73], v[174:177]
	v_mfma_f32_16x16x32_bf16 v[70:73], v[240:243], v[170:173], v[10:13]
	v_mfma_f32_16x16x32_bf16 v[10:13], v[218:221], v[194:197], v[206:209]
	v_mfma_f32_16x16x32_bf16 v[34:37], v[222:225], v[198:201], v[10:13]
	v_mfma_f32_16x16x32_bf16 v[10:13], v[236:239], v[194:197], v[178:181]
	v_mfma_f32_16x16x32_bf16 v[38:41], v[240:243], v[198:201], v[10:13]
	v_mfma_f32_16x16x32_bf16 v[10:13], v[218:221], v[210:213], v[182:185]
	v_mfma_f32_16x16x32_bf16 v[14:17], v[236:239], v[210:213], v[162:165]
	v_mfma_f32_16x16x32_bf16 v[10:13], v[222:225], v[214:217], v[10:13]
	v_mfma_f32_16x16x32_bf16 v[14:17], v[240:243], v[214:217], v[14:17]
	s_setprio 0
	s_barrier
	s_andn2_b64 vcc, exec, s[8:9]
	s_cbranch_vccnz .LBB0_300
	s_barrier

; #define PG8_STAGE(bufoff, gbase, voff) do { _Pragma("unroll") for (int _i = 0; _i < 2; ++_i) \
;         __builtin_amdgcn_global_load_lds((const unsigned*)((const char*)(gbase) + (voff)[_i]), (LAS unsigned*)(lds + (bufoff) + ldsw + _i * 8192), 16, 0, 0); } while (0)
; #define PG8_WAIT_V(n) asm volatile("s_waitcnt vmcnt(" #n ")" ::: "memory")
; #define PG8_BAR __builtin_amdgcn_s_barrier()
; #define FRESH() const int lane = fresh_lane(); int wave = wave_s; asm volatile("" : "+s"(wave)); const int tid = wave * 64 + lane; (void)tid; unsigned char* ws = p.ws; asm volatile("" : "+s"(ws)); (void)ws; Params pl = p; pl.ws = ws; (void)pl
; template <class Epi, bool PERM = true, bool DBLK = false>
; __device__ __forceinline__ void gemm_phase(LAS unsigned char* lds, const Gemm g, const StaticOrder& S, const Epi& E, const int tid) {
;     ...
;     Unit cur, nxt; int ui = 0;
;     if (!S.next(0, cur)) return;
;     f32x4 acc[2][2][4][2];
; #pragma unroll
;     for (int a = 0; a < 2; ++a)
; #pragma unroll
;         for (int b = 0; b < 2; ++b)
; #pragma unroll
;             for (int m = 0; m < 4; ++m)
; #pragma unroll
;                 for (int n = 0; n < 2; ++n) acc[a][b][m][n] = (f32x4){0.f, 0.f, 0.f, 0.f};
;     bf16x8 At[4][2], B0[2][2], B1[2][2];
;     const char* cA = (const char*)g.A + (size_t)cur.pm * tstep; const char* cB = (const char*)g.Bt + (size_t)cur.pn * tstep;
;     PG8_STAGE(PG8_SB(0, 0), cB, voffB); PG8_STAGE(PG8_SB(0, 1), cB + hstep, voffB); PG8_STAGE(PG8_SA(0, 0), cA, voffA); PG8_STAGE(PG8_SA(0, 1), cA + hstep, voffA);
;     if (wr == 1) PG8_BAR;
;     PG8_WAIT_V(2); PG8_BAR;
;     PG8_STAGE(PG8_SB(1, 0), cB + kstep, voffB); PG8_STAGE(PG8_SA(1, 0), cA + kstep, voffA); PG8_STAGE(PG8_SB(1, 1), cB + hstep + kstep, voffB);
;     PG8_WAIT_V(6); PG8_BAR;
; __global__ void __launch_bounds__(512, 2) hymba_fwd(Params p) {
;     ...
;         for (int rep = 0; rep < (((DUPMASK & 256) && l == 0) ? 2 : 1); ++rep) { FRESH(); float* SSQ = (float*)(ws + WS_SSQ);
;             pg8::Gemm g{(const bf16_t*)(ws + WS_KVR), (const bf16_t*)(ws + WS_WOUT) + (size_t)l * DM * DM, T, DM, DM};
;             pg8::StaticOrder S; S.init(T, DM, G, bx);
;             const bool lastl = (l == DEPTH - 1);
;             EpiOut E{l == 0 ? p.x : p.out, p.out, lastl ? nullptr : (bf16_t*)(ws + WS_XB), lastl ? nullptr : SSQ};
.LBB0_520:
	v_readlane_b32 s12, v254, 2
	s_cmp_eq_u32 s60, 0
	v_readlane_b32 s13, v254, 3
	v_readlane_b32 s14, v254, 4
	v_readlane_b32 s15, v254, 5
	s_cselect_b32 s15, s13, s49
	s_cselect_b32 s14, s12, s48
	s_add_u32 s10, s0, 0x2500000
	s_addc_u32 s11, s1, 0
	s_add_u32 s12, s0, 0x2600000
	s_addc_u32 s13, s1, 0
	v_and_b32_e32 v17, 48, v11
	s_waitcnt vmcnt(0)
	v_lshlrev_b32_e32 v18, 6, v11
	s_movk_i32 s1, 0x3c0
	v_lshlrev_b32_e32 v11, 2, v11
	s_and_b32 s62, s28, 3
	s_lshl_b32 s0, s5, 13
	v_and_or_b32 v17, v18, s1, v17
	v_and_b32_e32 v11, 32, v11
	s_add_i32 m0, s3, 0x18000
	v_lshl_add_u64 v[8:9], v[8:9], 0, s[84:85]
	s_lshl_b32 s59, s5, 6
	v_bitop3_b32 v18, v17, s0, v11 bitop3:0xde
	s_lshl_b32 s63, s62, 5
	s_lshl_b32 s0, s62, 12
	s_waitcnt vmcnt(2)
	s_barrier
	global_load_lds_dwordx4 v[8:9], off
	v_lshl_add_u64 v[6:7], v[6:7], 0, s[84:85]
	s_add_i32 m0, s3, 0x1a000
	s_add_i32 s66, s3, 0x8000
	s_add_i32 s67, s3, 0xa000
	v_bitop3_b32 v235, s0, v17, v11 bitop3:0xf6
	global_load_lds_dwordx4 v[6:7], off
	v_lshl_add_u64 v[2:3], v[2:3], 0, s[84:85]
	s_mov_b32 m0, s66
	s_add_u32 s0, s30, 0x40080
	global_load_lds_dwordx4 v[2:3], off
	v_lshl_add_u64 v[2:3], v[4:5], 0, s[84:85]
	s_mov_b32 m0, s67
	s_addc_u32 s1, s31, 0
	global_load_lds_dwordx4 v[2:3], off
	s_add_i32 m0, s3, 0x1c000
	s_nop 0
	global_load_lds_dwordx4 v0, s[0:1]
	v_lshl_add_u64 v[2:3], s[0:1], 0, v[202:203]
	s_add_i32 m0, s3, 0x1e000
	v_readlane_b32 s16, v254, 6
	global_load_lds_dwordx4 v[2:3], off
	v_lshlrev_b32_e32 v2, 14, v10
	v_and_b32_e32 v2, 0xffff8000, v2
	v_lshl_add_u32 v2, v12, 11, v2
	v_and_b32_e32 v3, 1, v10
	v_lshl_or_b32 v2, v3, 6, v2
	v_lshl_add_u32 v204, v13, 1, v2
	v_lshlrev_b32_e32 v2, 14, v14
	v_and_b32_e32 v2, 0xffff8000, v2
	v_lshl_add_u32 v2, v15, 11, v2
	v_and_b32_e32 v3, 1, v14
	s_waitcnt vmcnt(6)
	v_lshl_or_b32 v2, v3, 6, v2
	v_readlane_b32 s18, v254, 8
	v_readlane_b32 s19, v254, 9
	s_cmpk_lt_u32 s4, 0x100
	v_lshl_add_u32 v206, v16, 1, v2
	v_mov_b32_e32 v2, 0
	v_readlane_b32 s0, v255, 26
	s_mov_b32 s75, 0
	v_readlane_b32 s22, v254, 12
	v_readlane_b32 s24, v254, 14
	s_cselect_b64 s[18:19], -1, 0
	v_mov_b32_e32 v205, v1
	v_mov_b32_e32 v207, v1
	v_add_u32_e32 v236, 0, v18
	v_readlane_b32 s73, v255, 23
	s_mov_b32 s74, s0
	v_mov_b32_e32 v3, v2
	v_mov_b32_e32 v4, v2
	v_mov_b32_e32 v5, v2
	v_mov_b32_e32 v6, v2
	v_mov_b32_e32 v7, v2
	v_mov_b32_e32 v8, v2
	v_mov_b32_e32 v9, v2
	v_mov_b32_e32 v18, v2
	v_mov_b32_e32 v19, v2
	v_mov_b32_e32 v20, v2
	v_mov_b32_e32 v21, v2
	v_mov_b32_e32 v22, v2
	v_mov_b32_e32 v23, v2
	v_mov_b32_e32 v24, v2
	v_mov_b32_e32 v25, v2
	v_mov_b32_e32 v34, v2
	v_mov_b32_e32 v35, v2
	v_mov_b32_e32 v36, v2
	v_mov_b32_e32 v37, v2
	v_mov_b32_e32 v38, v2
	v_mov_b32_e32 v39, v2
	v_mov_b32_e32 v40, v2
	v_mov_b32_e32 v41, v2
	v_mov_b32_e32 v50, v2
	v_mov_b32_e32 v51, v2
	v_mov_b32_e32 v52, v2
	v_mov_b32_e32 v53, v2
	v_mov_b32_e32 v54, v2
	v_mov_b32_e32 v55, v2
	v_mov_b32_e32 v56, v2
	v_mov_b32_e32 v57, v2
	v_mov_b32_e32 v10, v2
	v_mov_b32_e32 v11, v2
	v_mov_b32_e32 v12, v2
	v_mov_b32_e32 v13, v2
	v_mov_b32_e32 v14, v2
	v_mov_b32_e32 v15, v2
	v_mov_b32_e32 v16, v2
	v_mov_b32_e32 v17, v2
	v_mov_b32_e32 v26, v2
	v_mov_b32_e32 v27, v2
	v_mov_b32_e32 v28, v2
	v_mov_b32_e32 v29, v2
	v_mov_b32_e32 v30, v2
	v_mov_b32_e32 v31, v2
	v_mov_b32_e32 v32, v2
	v_mov_b32_e32 v33, v2
	v_mov_b32_e32 v42, v2
	v_mov_b32_e32 v43, v2
	v_mov_b32_e32 v44, v2
	v_mov_b32_e32 v45, v2
	v_mov_b32_e32 v46, v2
	v_mov_b32_e32 v47, v2
	v_mov_b32_e32 v48, v2
	v_mov_b32_e32 v49, v2
	v_mov_b32_e32 v58, v2
	v_mov_b32_e32 v59, v2
	v_mov_b32_e32 v60, v2
	v_mov_b32_e32 v61, v2
	v_mov_b32_e32 v62, v2
	v_mov_b32_e32 v63, v2
	v_mov_b32_e32 v64, v2
	v_mov_b32_e32 v65, v2
	v_mov_b32_e32 v66, v2
	v_mov_b32_e32 v67, v2
	v_mov_b32_e32 v68, v2
	v_mov_b32_e32 v69, v2
	v_mov_b32_e32 v70, v2
	v_mov_b32_e32 v71, v2
	v_mov_b32_e32 v72, v2
	v_mov_b32_e32 v73, v2
	v_mov_b32_e32 v82, v2
	v_mov_b32_e32 v83, v2
	v_mov_b32_e32 v84, v2
	v_mov_b32_e32 v85, v2
	v_mov_b32_e32 v86, v2
	v_mov_b32_e32 v87, v2
	v_mov_b32_e32 v88, v2
	v_mov_b32_e32 v89, v2
	v_mov_b32_e32 v98, v2
	v_mov_b32_e32 v99, v2
	v_mov_b32_e32 v100, v2
	v_mov_b32_e32 v101, v2
	v_mov_b32_e32 v102, v2
	v_mov_b32_e32 v103, v2
	v_mov_b32_e32 v104, v2
	v_mov_b32_e32 v105, v2
	v_mov_b32_e32 v114, v2
	v_mov_b32_e32 v115, v2
	v_mov_b32_e32 v116, v2
	v_mov_b32_e32 v117, v2
	v_mov_b32_e32 v118, v2
	v_mov_b32_e32 v119, v2
	v_mov_b32_e32 v120, v2
	v_mov_b32_e32 v121, v2
	v_mov_b32_e32 v74, v2
	v_mov_b32_e32 v75, v2
	v_mov_b32_e32 v76, v2
	v_mov_b32_e32 v77, v2
	v_mov_b32_e32 v78, v2
	v_mov_b32_e32 v79, v2
	v_mov_b32_e32 v80, v2
	v_mov_b32_e32 v81, v2
	v_mov_b32_e32 v90, v2
	v_mov_b32_e32 v91, v2
	v_mov_b32_e32 v92, v2
	v_mov_b32_e32 v93, v2
	v_mov_b32_e32 v94, v2
	v_mov_b32_e32 v95, v2
	v_mov_b32_e32 v96, v2
	v_mov_b32_e32 v97, v2
	v_mov_b32_e32 v106, v2
	v_mov_b32_e32 v107, v2
	v_mov_b32_e32 v108, v2
	v_mov_b32_e32 v109, v2
	v_mov_b32_e32 v110, v2
	v_mov_b32_e32 v111, v2
	v_mov_b32_e32 v112, v2
	v_mov_b32_e32 v113, v2
	v_mov_b32_e32 v122, v2
	v_mov_b32_e32 v123, v2
	v_mov_b32_e32 v124, v2
	v_mov_b32_e32 v125, v2
	v_mov_b32_e32 v126, v2
	v_mov_b32_e32 v127, v2
	v_mov_b32_e32 v128, v2
	v_mov_b32_e32 v129, v2
	v_readlane_b32 s16, v255, 7
	v_readlane_b32 s17, v254, 7
	v_readlane_b32 s20, v254, 10
	v_readlane_b32 s21, v254, 11
	v_readlane_b32 s23, v254, 13
	v_readlane_b32 s25, v254, 15
	v_readlane_b32 s26, v254, 16
	v_readlane_b32 s27, v254, 17
	s_barrier
	v_readlane_b32 s1, v255, 27

; #define PG8_STAGE(bufoff, gbase, voff) do { _Pragma("unroll") for (int _i = 0; _i < 2; ++_i) \
;         __builtin_amdgcn_global_load_lds((const unsigned*)((const char*)(gbase) + (voff)[_i]), (LAS unsigned*)(lds + (bufoff) + ldsw + _i * 8192), 16, 0, 0); } while (0)
; #define PG8_LDA(dst, b, h) do { _Pragma("unroll") for (int m = 0; m < 4; ++m) _Pragma("unroll") for (int k = 0; k < 2; ++k) dst[m][k] = *(const LAS bf16x8*)(lds + PG8_SA(b, h) + aoff + m * 2048 + k * 1024); } while (0)
; #define PG8_LDB(dst, b, h) do { _Pragma("unroll") for (int n = 0; n < 2; ++n) _Pragma("unroll") for (int k = 0; k < 2; ++k) dst[n][k] = *(const LAS bf16x8*)(lds + PG8_SB(b, h) + boff + n * 2048 + k * 1024); } while (0)
; #define PG8_MMA(ai, bj, At, Bt) do { __builtin_amdgcn_s_setprio(1); _Pragma("unroll") for (int m = 0; m < 4; ++m) _Pragma("unroll") for (int n = 0; n < 2; ++n) _Pragma("unroll") for (int k = 0; k < 2; ++k) \
;         acc[ai][bj][m][n] = __builtin_amdgcn_mfma_f32_16x16x32_bf16(Bt[n][k], At[m][k], acc[ai][bj][m][n], 0, 0, 0); __builtin_amdgcn_s_setprio(0); } while (0)
; #define PG8_WAIT_V(n) asm volatile("s_waitcnt vmcnt(" #n ")" ::: "memory")
; #define PG8_WAIT_L(n) asm volatile("s_waitcnt lgkmcnt(" #n ")" ::: "memory")
; #define PG8_BAR __builtin_amdgcn_s_barrier()
; #define PG8_SCHED __builtin_amdgcn_sched_barrier(0)
; template <class Epi, bool PERM = true, bool DBLK = false>
; __device__ __forceinline__ void gemm_phase(LAS unsigned char* lds, const Gemm g, const StaticOrder& S, const Epi& E, const int tid) {
;     ...
;             const char* a1 = cA + (size_t)(t + 1) * kstep;
;             const char* a2 = last ? nA : (lastp ? cA : cA + (size_t)(t + 2) * kstep); const char* b2 = last ? nB : (lastp ? cB : cB + (size_t)(t + 2) * kstep);
;             const char* a3 = a2 + kstep; const char* b3 = b2 + kstep;
;             PG8_LDB(B0, 0, 0); PG8_LDB(B1, 0, 1); PG8_SCHED; PG8_LDA(At, 0, 0); PG8_STAGE(PG8_SA(1, 1), a1 + hstep, voffA);
;             PG8_WAIT_V(8); PG8_WAIT_L(0); PG8_BAR; PG8_MMA(0, 0, At, B0); PG8_MMA(0, 1, At, B1); PG8_BAR; PG8_SCHED;
;             PG8_LDA(At, 0, 1); PG8_STAGE(PG8_SB(0, 0), b2, voffB); PG8_STAGE(PG8_SB(0, 1), b2 + hstep, voffB); PG8_STAGE(PG8_SA(0, 0), a2, voffA);
;             PG8_WAIT_V(8); PG8_WAIT_L(0); PG8_BAR; PG8_MMA(1, 0, At, B0); PG8_MMA(1, 1, At, B1); PG8_BAR; PG8_SCHED;
.LBB0_528:
	s_add_u32 s34, s6, s30
	s_addc_u32 s35, s7, s31
	s_add_u32 s34, s34, 0x100
	s_addc_u32 s35, s35, 0
	s_add_u32 s64, s78, s30
	s_addc_u32 s80, s79, s31
	s_add_i32 s81, 0, 0x10000
	s_cmpk_eq_i32 s30, 0x700
	s_cselect_b32 s53, s25, s35
	s_cselect_b32 s52, s86, s34
	s_cselect_b32 s35, s23, s80
	s_cselect_b32 s34, s82, s64
	s_add_i32 s64, 0, 0x14000
	v_add_u32_e32 v146, s81, v235
	v_add_u32_e32 v162, s64, v235
	ds_read_b128 v[134:137], v146
	ds_read_b128 v[138:141], v146 offset:1024
	ds_read_b128 v[142:145], v146 offset:2048
	ds_read_b128 v[146:149], v146 offset:3072
	ds_read_b128 v[150:153], v162
	ds_read_b128 v[154:157], v162 offset:1024
	ds_read_b128 v[158:161], v162 offset:2048
	ds_read_b128 v[162:165], v162 offset:3072
	v_lshl_add_u64 v[198:199], v[132:133], 0, s[30:31]
	s_add_i32 m0, s3, 0xc000
	ds_read_b128 v[166:169], v236
	ds_read_b128 v[170:173], v236 offset:1024
	ds_read_b128 v[174:177], v236 offset:2048
	ds_read_b128 v[178:181], v236 offset:3072
	ds_read_b128 v[182:185], v236 offset:4096
	ds_read_b128 v[186:189], v236 offset:5120
	ds_read_b128 v[190:193], v236 offset:6144
	ds_read_b128 v[194:197], v236 offset:7168
	global_load_lds_dwordx4 v[198:199], off
	v_lshl_add_u64 v[198:199], v[130:131], 0, s[30:31]
	s_add_i32 m0, s3, 0xe000
	s_nop 0
	global_load_lds_dwordx4 v[198:199], off
	s_waitcnt vmcnt(8)
	s_waitcnt lgkmcnt(0)
	s_barrier
	s_setprio 1
	s_waitcnt lgkmcnt(0)
	v_mfma_f32_16x16x32_bf16 v[126:129], v[134:137], v[166:169], v[126:129]
	v_mfma_f32_16x16x32_bf16 v[122:125], v[142:145], v[166:169], v[122:125]
	v_mfma_f32_16x16x32_bf16 v[110:113], v[134:137], v[174:177], v[110:113]
	v_mfma_f32_16x16x32_bf16 v[106:109], v[142:145], v[174:177], v[106:109]
	v_mfma_f32_16x16x32_bf16 v[94:97], v[134:137], v[182:185], v[94:97]
	v_mfma_f32_16x16x32_bf16 v[90:93], v[142:145], v[182:185], v[90:93]
	v_mfma_f32_16x16x32_bf16 v[78:81], v[134:137], v[190:193], v[78:81]
	v_mfma_f32_16x16x32_bf16 v[74:77], v[142:145], v[190:193], v[74:77]
	v_mfma_f32_16x16x32_bf16 v[126:129], v[138:141], v[170:173], v[126:129]
	v_mfma_f32_16x16x32_bf16 v[122:125], v[146:149], v[170:173], v[122:125]
	v_mfma_f32_16x16x32_bf16 v[110:113], v[138:141], v[178:181], v[110:113]
	v_mfma_f32_16x16x32_bf16 v[106:109], v[146:149], v[178:181], v[106:109]
	v_mfma_f32_16x16x32_bf16 v[94:97], v[138:141], v[186:189], v[94:97]
	v_mfma_f32_16x16x32_bf16 v[90:93], v[146:149], v[186:189], v[90:93]
	v_mfma_f32_16x16x32_bf16 v[78:81], v[138:141], v[194:197], v[78:81]
	v_mfma_f32_16x16x32_bf16 v[74:77], v[146:149], v[194:197], v[74:77]
	s_setprio 0
	s_setprio 1
	v_mfma_f32_16x16x32_bf16 v[118:121], v[150:153], v[166:169], v[118:121]
	v_mfma_f32_16x16x32_bf16 v[114:117], v[158:161], v[166:169], v[114:117]
	v_mfma_f32_16x16x32_bf16 v[102:105], v[150:153], v[174:177], v[102:105]
	v_mfma_f32_16x16x32_bf16 v[98:101], v[158:161], v[174:177], v[98:101]
	v_mfma_f32_16x16x32_bf16 v[86:89], v[150:153], v[182:185], v[86:89]
	v_mfma_f32_16x16x32_bf16 v[82:85], v[158:161], v[182:185], v[82:85]
	v_mfma_f32_16x16x32_bf16 v[70:73], v[150:153], v[190:193], v[70:73]
	v_mfma_f32_16x16x32_bf16 v[66:69], v[158:161], v[190:193], v[66:69]
	v_mfma_f32_16x16x32_bf16 v[118:121], v[154:157], v[170:173], v[118:121]
	v_mfma_f32_16x16x32_bf16 v[114:117], v[162:165], v[170:173], v[114:117]
	v_mfma_f32_16x16x32_bf16 v[102:105], v[154:157], v[178:181], v[102:105]
	v_mfma_f32_16x16x32_bf16 v[98:101], v[162:165], v[178:181], v[98:101]
	v_mfma_f32_16x16x32_bf16 v[86:89], v[154:157], v[186:189], v[86:89]
	v_mfma_f32_16x16x32_bf16 v[82:85], v[162:165], v[186:189], v[82:85]
	v_mfma_f32_16x16x32_bf16 v[70:73], v[154:157], v[194:197], v[70:73]
	v_mfma_f32_16x16x32_bf16 v[66:69], v[162:165], v[194:197], v[66:69]
	s_setprio 0
	s_barrier
	s_add_i32 s80, s81, s54
	v_lshl_add_u64 v[198:199], s[34:35], 0, v[0:1]
	s_mov_b32 m0, s80
	ds_read_b128 v[166:169], v236 offset:16384
	ds_read_b128 v[170:173], v236 offset:17408
	ds_read_b128 v[174:177], v236 offset:18432
	ds_read_b128 v[178:181], v236 offset:19456
	ds_read_b128 v[182:185], v236 offset:20480
	ds_read_b128 v[186:189], v236 offset:21504
	ds_read_b128 v[190:193], v236 offset:22528
	ds_read_b128 v[194:197], v236 offset:23552
	global_load_lds_dwordx4 v[198:199], off
	s_add_i32 m0, s80, 0x2000
	s_add_u32 s80, s34, 0x40000
	v_lshl_add_u64 v[200:201], s[34:35], 0, v[202:203]
	s_addc_u32 s81, s35, 0
	s_add_i32 s64, s64, s54
	global_load_lds_dwordx4 v[200:201], off
	s_mov_b32 m0, s64
	v_lshl_add_u64 v[210:211], s[52:53], 0, v[202:203]
	global_load_lds_dwordx4 v0, s[80:81]
	s_add_i32 m0, s64, 0x2000
	s_nop 0
	global_load_lds_dwordx4 v202, s[80:81]
	v_lshl_add_u64 v[208:209], s[52:53], 0, v[0:1]
	s_mov_b32 m0, s3
	s_nop 0
	global_load_lds_dwordx4 v[208:209], off
	s_mov_b32 m0, s55
	s_nop 0
	global_load_lds_dwordx4 v[210:211], off
	s_waitcnt vmcnt(8)
	s_waitcnt lgkmcnt(0)
	s_barrier
; #define PG8_STAGE(bufoff, gbase, voff) do { _Pragma("unroll") for (int _i = 0; _i < 2; ++_i) \
;         __builtin_amdgcn_global_load_lds((const unsigned*)((const char*)(gbase) + (voff)[_i]), (LAS unsigned*)(lds + (bufoff) + ldsw + _i * 8192), 16, 0, 0); } while (0)
; #define PG8_LDA(dst, b, h) do { _Pragma("unroll") for (int m = 0; m < 4; ++m) _Pragma("unroll") for (int k = 0; k < 2; ++k) dst[m][k] = *(const LAS bf16x8*)(lds + PG8_SA(b, h) + aoff + m * 2048 + k * 1024); } while (0)
; #define PG8_LDB(dst, b, h) do { _Pragma("unroll") for (int n = 0; n < 2; ++n) _Pragma("unroll") for (int k = 0; k < 2; ++k) dst[n][k] = *(const LAS bf16x8*)(lds + PG8_SB(b, h) + boff + n * 2048 + k * 1024); } while (0)
; #define PG8_MMA(ai, bj, At, Bt) do { __builtin_amdgcn_s_setprio(1); _Pragma("unroll") for (int m = 0; m < 4; ++m) _Pragma("unroll") for (int n = 0; n < 2; ++n) _Pragma("unroll") for (int k = 0; k < 2; ++k) \
;         acc[ai][bj][m][n] = __builtin_amdgcn_mfma_f32_16x16x32_bf16(Bt[n][k], At[m][k], acc[ai][bj][m][n], 0, 0, 0); __builtin_amdgcn_s_setprio(0); } while (0)
; #define PG8_WAIT_V(n) asm volatile("s_waitcnt vmcnt(" #n ")" ::: "memory")
; #define PG8_WAIT_L(n) asm volatile("s_waitcnt lgkmcnt(" #n ")" ::: "memory")
; #define PG8_BAR __builtin_amdgcn_s_barrier()
; #define PG8_SCHED __builtin_amdgcn_sched_barrier(0)
; template <class Epi, bool PERM = true, bool DBLK = false>
; __device__ __forceinline__ void gemm_phase(LAS unsigned char* lds, const Gemm g, const StaticOrder& S, const Epi& E, const int tid) {
;     ...
;             PG8_WAIT_V(8); PG8_WAIT_L(0); PG8_BAR; PG8_MMA(1, 0, At, B0); PG8_MMA(1, 1, At, B1); PG8_BAR; PG8_SCHED;
;             PG8_LDB(B0, 1, 0); PG8_LDB(B1, 1, 1); PG8_SCHED; PG8_LDA(At, 1, 0); PG8_STAGE(PG8_SA(0, 1), a2 + hstep, voffA);
;             PG8_WAIT_V(8); PG8_WAIT_L(0); PG8_BAR; PG8_MMA(0, 0, At, B0); PG8_MMA(0, 1, At, B1); PG8_BAR; PG8_SCHED;
	s_setprio 1
	s_waitcnt lgkmcnt(0)
	v_mfma_f32_16x16x32_bf16 v[62:65], v[134:137], v[166:169], v[62:65]
	v_mfma_f32_16x16x32_bf16 v[58:61], v[142:145], v[166:169], v[58:61]
	v_mfma_f32_16x16x32_bf16 v[46:49], v[134:137], v[174:177], v[46:49]
	v_mfma_f32_16x16x32_bf16 v[42:45], v[142:145], v[174:177], v[42:45]
	v_mfma_f32_16x16x32_bf16 v[30:33], v[134:137], v[182:185], v[30:33]
	v_mfma_f32_16x16x32_bf16 v[26:29], v[142:145], v[182:185], v[26:29]
	v_mfma_f32_16x16x32_bf16 v[14:17], v[134:137], v[190:193], v[14:17]
	v_mfma_f32_16x16x32_bf16 v[10:13], v[142:145], v[190:193], v[10:13]
	v_mfma_f32_16x16x32_bf16 v[62:65], v[138:141], v[170:173], v[62:65]
	v_mfma_f32_16x16x32_bf16 v[58:61], v[146:149], v[170:173], v[58:61]
	v_mfma_f32_16x16x32_bf16 v[46:49], v[138:141], v[178:181], v[46:49]
	v_mfma_f32_16x16x32_bf16 v[42:45], v[146:149], v[178:181], v[42:45]
	v_mfma_f32_16x16x32_bf16 v[30:33], v[138:141], v[186:189], v[30:33]
	v_mfma_f32_16x16x32_bf16 v[26:29], v[146:149], v[186:189], v[26:29]
	v_mfma_f32_16x16x32_bf16 v[14:17], v[138:141], v[194:197], v[14:17]
	v_mfma_f32_16x16x32_bf16 v[10:13], v[146:149], v[194:197], v[10:13]
	s_setprio 0
	s_setprio 1
	v_mfma_f32_16x16x32_bf16 v[54:57], v[150:153], v[166:169], v[54:57]
	v_mfma_f32_16x16x32_bf16 v[50:53], v[158:161], v[166:169], v[50:53]
	v_mfma_f32_16x16x32_bf16 v[38:41], v[150:153], v[174:177], v[38:41]
	v_mfma_f32_16x16x32_bf16 v[34:37], v[158:161], v[174:177], v[34:37]
	v_mfma_f32_16x16x32_bf16 v[22:25], v[150:153], v[182:185], v[22:25]
	v_mfma_f32_16x16x32_bf16 v[18:21], v[158:161], v[182:185], v[18:21]
	v_mfma_f32_16x16x32_bf16 v[6:9], v[150:153], v[190:193], v[6:9]
	v_mfma_f32_16x16x32_bf16 v[2:5], v[158:161], v[190:193], v[2:5]
	v_mfma_f32_16x16x32_bf16 v[54:57], v[154:157], v[170:173], v[54:57]
	v_mfma_f32_16x16x32_bf16 v[50:53], v[162:165], v[170:173], v[50:53]
	v_mfma_f32_16x16x32_bf16 v[38:41], v[154:157], v[178:181], v[38:41]
	v_mfma_f32_16x16x32_bf16 v[34:37], v[162:165], v[178:181], v[34:37]
	v_mfma_f32_16x16x32_bf16 v[22:25], v[154:157], v[186:189], v[22:25]
	v_mfma_f32_16x16x32_bf16 v[18:21], v[162:165], v[186:189], v[18:21]
	v_mfma_f32_16x16x32_bf16 v[6:9], v[154:157], v[194:197], v[6:9]
	v_mfma_f32_16x16x32_bf16 v[2:5], v[162:165], v[194:197], v[2:5]
	s_setprio 0
	s_barrier
	s_add_i32 s64, 0, 0x18000
	s_add_i32 s80, 0, 0x1c000
	v_add_u32_e32 v146, s64, v235
	v_add_u32_e32 v162, s80, v235
	ds_read_b128 v[134:137], v146
	ds_read_b128 v[138:141], v146 offset:1024
	ds_read_b128 v[142:145], v146 offset:2048
	ds_read_b128 v[146:149], v146 offset:3072
	ds_read_b128 v[150:153], v162
	ds_read_b128 v[154:157], v162 offset:1024
	ds_read_b128 v[158:161], v162 offset:2048
	ds_read_b128 v[162:165], v162 offset:3072
	s_add_u32 s52, s52, 0x40000
	s_addc_u32 s53, s53, 0
	s_mov_b32 m0, s56
	ds_read_b128 v[166:169], v236 offset:32768
	ds_read_b128 v[170:173], v236 offset:33792
	ds_read_b128 v[174:177], v236 offset:34816
	ds_read_b128 v[178:181], v236 offset:35840
	ds_read_b128 v[182:185], v236 offset:36864
	ds_read_b128 v[186:189], v236 offset:37888
	ds_read_b128 v[190:193], v236 offset:38912
	ds_read_b128 v[194:197], v236 offset:39936
	global_load_lds_dwordx4 v0, s[52:53]
	v_lshl_add_u64 v[212:213], s[52:53], 0, v[202:203]
	s_mov_b32 m0, s57
	s_nop 0
	global_load_lds_dwordx4 v[212:213], off
	s_waitcnt vmcnt(8)
	s_waitcnt lgkmcnt(0)
	s_barrier
	s_setprio 1
	s_waitcnt lgkmcnt(0)
	v_mfma_f32_16x16x32_bf16 v[126:129], v[134:137], v[166:169], v[126:129]
	v_mfma_f32_16x16x32_bf16 v[122:125], v[142:145], v[166:169], v[122:125]
	v_mfma_f32_16x16x32_bf16 v[110:113], v[134:137], v[174:177], v[110:113]
	v_mfma_f32_16x16x32_bf16 v[106:109], v[142:145], v[174:177], v[106:109]
	v_mfma_f32_16x16x32_bf16 v[94:97], v[134:137], v[182:185], v[94:97]
	v_mfma_f32_16x16x32_bf16 v[90:93], v[142:145], v[182:185], v[90:93]
	v_mfma_f32_16x16x32_bf16 v[78:81], v[134:137], v[190:193], v[78:81]
	v_mfma_f32_16x16x32_bf16 v[74:77], v[142:145], v[190:193], v[74:77]
	v_mfma_f32_16x16x32_bf16 v[126:129], v[138:141], v[170:173], v[126:129]
	v_mfma_f32_16x16x32_bf16 v[122:125], v[146:149], v[170:173], v[122:125]
	v_mfma_f32_16x16x32_bf16 v[110:113], v[138:141], v[178:181], v[110:113]
	v_mfma_f32_16x16x32_bf16 v[106:109], v[146:149], v[178:181], v[106:109]
	v_mfma_f32_16x16x32_bf16 v[94:97], v[138:141], v[186:189], v[94:97]
	v_mfma_f32_16x16x32_bf16 v[90:93], v[146:149], v[186:189], v[90:93]
	v_mfma_f32_16x16x32_bf16 v[78:81], v[138:141], v[194:197], v[78:81]
	v_mfma_f32_16x16x32_bf16 v[74:77], v[146:149], v[194:197], v[74:77]
	s_setprio 0
	s_setprio 1
	v_mfma_f32_16x16x32_bf16 v[118:121], v[150:153], v[166:169], v[118:121]
	v_mfma_f32_16x16x32_bf16 v[114:117], v[158:161], v[166:169], v[114:117]
	v_mfma_f32_16x16x32_bf16 v[102:105], v[150:153], v[174:177], v[102:105]
	v_mfma_f32_16x16x32_bf16 v[98:101], v[158:161], v[174:177], v[98:101]
	v_mfma_f32_16x16x32_bf16 v[86:89], v[150:153], v[182:185], v[86:89]
	v_mfma_f32_16x16x32_bf16 v[82:85], v[158:161], v[182:185], v[82:85]
	v_mfma_f32_16x16x32_bf16 v[70:73], v[150:153], v[190:193], v[70:73]
	v_mfma_f32_16x16x32_bf16 v[66:69], v[158:161], v[190:193], v[66:69]
	v_mfma_f32_16x16x32_bf16 v[118:121], v[154:157], v[170:173], v[118:121]
	v_mfma_f32_16x16x32_bf16 v[114:117], v[162:165], v[170:173], v[114:117]
	v_mfma_f32_16x16x32_bf16 v[102:105], v[154:157], v[178:181], v[102:105]
	v_mfma_f32_16x16x32_bf16 v[98:101], v[162:165], v[178:181], v[98:101]
	v_mfma_f32_16x16x32_bf16 v[86:89], v[154:157], v[186:189], v[86:89]
	v_mfma_f32_16x16x32_bf16 v[82:85], v[162:165], v[186:189], v[82:85]
	v_mfma_f32_16x16x32_bf16 v[70:73], v[154:157], v[194:197], v[70:73]
	v_mfma_f32_16x16x32_bf16 v[66:69], v[162:165], v[194:197], v[66:69]
	s_setprio 0
	s_barrier
; #define PG8_STAGE(bufoff, gbase, voff) do { _Pragma("unroll") for (int _i = 0; _i < 2; ++_i) \
;         __builtin_amdgcn_global_load_lds((const unsigned*)((const char*)(gbase) + (voff)[_i]), (LAS unsigned*)(lds + (bufoff) + ldsw + _i * 8192), 16, 0, 0); } while (0)
; #define PG8_LDA(dst, b, h) do { _Pragma("unroll") for (int m = 0; m < 4; ++m) _Pragma("unroll") for (int k = 0; k < 2; ++k) dst[m][k] = *(const LAS bf16x8*)(lds + PG8_SA(b, h) + aoff + m * 2048 + k * 1024); } while (0)
; #define PG8_MMA(ai, bj, At, Bt) do { __builtin_amdgcn_s_setprio(1); _Pragma("unroll") for (int m = 0; m < 4; ++m) _Pragma("unroll") for (int n = 0; n < 2; ++n) _Pragma("unroll") for (int k = 0; k < 2; ++k) \
;         acc[ai][bj][m][n] = __builtin_amdgcn_mfma_f32_16x16x32_bf16(Bt[n][k], At[m][k], acc[ai][bj][m][n], 0, 0, 0); __builtin_amdgcn_s_setprio(0); } while (0)
; #define PG8_WAIT_V(n) asm volatile("s_waitcnt vmcnt(" #n ")" ::: "memory")
; #define PG8_WAIT_L(n) asm volatile("s_waitcnt lgkmcnt(" #n ")" ::: "memory")
; #define PG8_BAR __builtin_amdgcn_s_barrier()
; #define PG8_SCHED __builtin_amdgcn_sched_barrier(0)
; template <class Epi, bool PERM = true, bool DBLK = false>
; __device__ __forceinline__ void gemm_phase(LAS unsigned char* lds, const Gemm g, const StaticOrder& S, const Epi& E, const int tid) {
;     ...
;             PG8_LDA(At, 1, 1); PG8_STAGE(PG8_SB(1, 0), b3, voffB); PG8_STAGE(PG8_SB(1, 1), b3 + hstep, voffB); PG8_STAGE(PG8_SA(1, 0), a3, voffA);
;             PG8_WAIT_V(8); PG8_WAIT_L(0); PG8_BAR; PG8_MMA(1, 0, At, B0); PG8_MMA(1, 1, At, B1); PG8_BAR; PG8_SCHED;
;         }
;         if (wr == 0) PG8_BAR;
	s_add_i32 s52, s64, s54
	v_lshl_add_u64 v[198:199], v[198:199], 0, s[84:85]
	s_mov_b32 m0, s52
	ds_read_b128 v[166:169], v236 offset:49152
	ds_read_b128 v[170:173], v236 offset:50176
	ds_read_b128 v[174:177], v236 offset:51200
	ds_read_b128 v[178:181], v236 offset:52224
	ds_read_b128 v[182:185], v236 offset:53248
	ds_read_b128 v[186:189], v236 offset:54272
	ds_read_b128 v[190:193], v236 offset:55296
	ds_read_b128 v[194:197], v236 offset:56320
	global_load_lds_dwordx4 v[198:199], off
	s_add_i32 m0, s52, 0x2000
	s_add_u32 s34, s34, 0x40080
	v_lshl_add_u64 v[198:199], v[200:201], 0, s[84:85]
	s_addc_u32 s35, s35, 0
	s_add_i32 s52, s80, s54
	global_load_lds_dwordx4 v[198:199], off
	s_mov_b32 m0, s52
	s_nop 0
	global_load_lds_dwordx4 v0, s[34:35]
	s_add_i32 m0, s52, 0x2000
	s_nop 0
	global_load_lds_dwordx4 v202, s[34:35]
	v_lshl_add_u64 v[198:199], v[208:209], 0, s[84:85]
	s_mov_b32 m0, s66
	s_nop 0
	global_load_lds_dwordx4 v[198:199], off
	v_lshl_add_u64 v[198:199], v[210:211], 0, s[84:85]
	s_mov_b32 m0, s67
	s_nop 0
	global_load_lds_dwordx4 v[198:199], off
	s_waitcnt vmcnt(8)
	s_waitcnt lgkmcnt(0)
	s_barrier
	s_setprio 1
	s_waitcnt lgkmcnt(0)
	v_mfma_f32_16x16x32_bf16 v[62:65], v[134:137], v[166:169], v[62:65]
	v_mfma_f32_16x16x32_bf16 v[58:61], v[142:145], v[166:169], v[58:61]
	v_mfma_f32_16x16x32_bf16 v[46:49], v[134:137], v[174:177], v[46:49]
	v_mfma_f32_16x16x32_bf16 v[42:45], v[142:145], v[174:177], v[42:45]
	v_mfma_f32_16x16x32_bf16 v[30:33], v[134:137], v[182:185], v[30:33]
	v_mfma_f32_16x16x32_bf16 v[26:29], v[142:145], v[182:185], v[26:29]
	v_mfma_f32_16x16x32_bf16 v[14:17], v[134:137], v[190:193], v[14:17]
	v_mfma_f32_16x16x32_bf16 v[10:13], v[142:145], v[190:193], v[10:13]
	v_mfma_f32_16x16x32_bf16 v[62:65], v[138:141], v[170:173], v[62:65]
	v_mfma_f32_16x16x32_bf16 v[58:61], v[146:149], v[170:173], v[58:61]
	v_mfma_f32_16x16x32_bf16 v[46:49], v[138:141], v[178:181], v[46:49]
	v_mfma_f32_16x16x32_bf16 v[42:45], v[146:149], v[178:181], v[42:45]
	v_mfma_f32_16x16x32_bf16 v[30:33], v[138:141], v[186:189], v[30:33]
	v_mfma_f32_16x16x32_bf16 v[26:29], v[146:149], v[186:189], v[26:29]
	v_mfma_f32_16x16x32_bf16 v[14:17], v[138:141], v[194:197], v[14:17]
	v_mfma_f32_16x16x32_bf16 v[10:13], v[146:149], v[194:197], v[10:13]
	s_setprio 0
	s_setprio 1
	v_mfma_f32_16x16x32_bf16 v[54:57], v[150:153], v[166:169], v[54:57]
	v_mfma_f32_16x16x32_bf16 v[50:53], v[158:161], v[166:169], v[50:53]
	v_mfma_f32_16x16x32_bf16 v[38:41], v[150:153], v[174:177], v[38:41]
	v_mfma_f32_16x16x32_bf16 v[34:37], v[158:161], v[174:177], v[34:37]
	v_mfma_f32_16x16x32_bf16 v[22:25], v[150:153], v[182:185], v[22:25]
	v_mfma_f32_16x16x32_bf16 v[18:21], v[158:161], v[182:185], v[18:21]
	v_mfma_f32_16x16x32_bf16 v[6:9], v[150:153], v[190:193], v[6:9]
	v_mfma_f32_16x16x32_bf16 v[2:5], v[158:161], v[190:193], v[2:5]
	v_mfma_f32_16x16x32_bf16 v[54:57], v[154:157], v[170:173], v[54:57]
	v_mfma_f32_16x16x32_bf16 v[50:53], v[162:165], v[170:173], v[50:53]
	v_mfma_f32_16x16x32_bf16 v[38:41], v[154:157], v[178:181], v[38:41]
	v_mfma_f32_16x16x32_bf16 v[34:37], v[162:165], v[178:181], v[34:37]
	v_mfma_f32_16x16x32_bf16 v[22:25], v[154:157], v[186:189], v[22:25]
	v_mfma_f32_16x16x32_bf16 v[18:21], v[162:165], v[186:189], v[18:21]
	v_mfma_f32_16x16x32_bf16 v[6:9], v[154:157], v[194:197], v[6:9]
	v_mfma_f32_16x16x32_bf16 v[2:5], v[162:165], v[194:197], v[2:5]
	s_setprio 0
	s_barrier
	s_add_i32 s83, s83, 2
	s_add_u32 s30, s30, 0x100
	s_addc_u32 s31, s31, 0
	s_cmp_gt_u32 s83, 13
	s_cbranch_scc0 .LBB0_528
	s_and_b64 vcc, exec, s[18:19]
	s_cbranch_vccz .LBB0_531
	s_barrier
